# V5 + GEMM 6-DMA load segments: A-tile LDS-DMA loads issued before the B-tile ones
# baseline (speedup 1.0000x reference)
; #define PG8_STAGE(bufoff, gbase, voff) do { _Pragma("unroll") for (int _i = 0; _i < 2; ++_i) \
;         __builtin_amdgcn_global_load_lds((const unsigned*)((const char*)(gbase) + (voff)[_i]), (PG8_LAS unsigned*)(lds + (bufoff) + ldsw + _i * 8192), 16, 0, 0); } while (0)
; #define PG8_LDA(dst, b, h) do { _Pragma("unroll") for (int m = 0; m < 4; ++m) _Pragma("unroll") for (int k = 0; k < 2; ++k) dst[m][k] = *(const PG8_LAS bf16x8*)(lds + PG8_SA(b, h) + aoff + m * 2048 + k * 1024); } while (0)
; #define PG8_LDB(dst, b, h) do { _Pragma("unroll") for (int n = 0; n < 2; ++n) _Pragma("unroll") for (int k = 0; k < 2; ++k) dst[n][k] = *(const PG8_LAS bf16x8*)(lds + PG8_SB(b, h) + boff + n * 2048 + k * 1024); } while (0)
; #define PG8_MMA(ai, bj, At, Bt) do { __builtin_amdgcn_s_setprio(1); _Pragma("unroll") for (int m = 0; m < 4; ++m) _Pragma("unroll") for (int n = 0; n < 2; ++n) _Pragma("unroll") for (int k = 0; k < 2; ++k) \
;         acc[ai][bj][m][n] = __builtin_amdgcn_mfma_f32_16x16x32_bf16(Bt[n][k], At[m][k], acc[ai][bj][m][n], 0, 0, 0); __builtin_amdgcn_s_setprio(0); } while (0)
; #define PG8_WAIT_V(n) asm volatile("s_waitcnt vmcnt(" #n ")" ::: "memory")
; #define PG8_WAIT_L(n) asm volatile("s_waitcnt lgkmcnt(" #n ")" ::: "memory")
; template <class Epi, class Sched, bool ALIGN_EPI = false, bool SP2 = false>
; __device__ __forceinline__ void gemm_phase(PG8_LAS unsigned char* lds, const Gemm g, const Sched& S, const Epi& E, int tid_in) {
;     ...
;             const bool last = (t == nt - 2);
;             const char* a1 = cA + (size_t)(t + 1) * kstep;
;             const char* a2 = last ? nA : cA + (size_t)(t + 2) * kstep; const char* b2 = last ? nB : cB + (size_t)(t + 2) * kstep;
;             const char* a3 = a2 + kstep; const char* b3 = b2 + kstep;
;             if (last && has_next) S.a_ready(nxt);
;             if constexpr (SP2) {
;             PG8_LDB(B0, 0, 0); PG8_LDB(B1, 0, 1); PG8_SCHED; PG8_LDA(At, 0, 0); PG8_STAGE(PG8_SA(1, 1), a1 + hstep, voffA);
;             PG8_WAIT_V(8); PG8_WAIT_L(0); PG8_BAR; PG8_MMA(0, 0, At, B0); PG8_MMA(0, 1, At, B1); PG8_BAR; PG8_SCHED;
;             PG8_LDA(At, 0, 1); PG8_STAGE(PG8_SB(0, 0), b2, voffB); PG8_STAGE(PG8_SB(0, 1), b2 + hstep, voffB); PG8_STAGE(PG8_SA(0, 0), a2, voffA);
;             PG8_WAIT_V(8); PG8_WAIT_L(0); PG8_BAR; PG8_MMA(1, 0, At, B0); PG8_MMA(1, 1, At, B1); PG8_BAR; PG8_SCHED;
.LBB0_376:
	s_add_u32 s26, s24, 0xfffc0080
	s_addc_u32 s27, s25, -1
	s_cmp_eq_u32 s56, 12
	s_cselect_b32 s29, s17, s27
	s_cselect_b32 s28, s52, s26
	s_cselect_b32 s27, s15, s55
	s_cselect_b32 s26, s53, s54
	s_add_i32 m0, s23, 0xc000
	ds_read_b128 v[150:153], v147
	global_load_lds_dwordx4 v136, s[24:25]
	s_add_i32 m0, s23, 0xe000
	ds_read_b128 v[154:157], v147 offset:1024
	global_load_lds_dwordx4 v138, s[24:25]
	ds_read_b128 v[158:161], v147 offset:2048
	ds_read_b128 v[162:165], v147 offset:3072
	ds_read_b128 v[166:169], v148
	ds_read_b128 v[170:173], v148 offset:1024
	ds_read_b128 v[174:177], v148 offset:2048
	ds_read_b128 v[178:181], v148 offset:3072
	ds_read_b128 v[182:185], v149
	ds_read_b128 v[186:189], v149 offset:1024
	ds_read_b128 v[190:193], v149 offset:2048
	ds_read_b128 v[194:197], v149 offset:3072
	ds_read_b128 v[198:201], v149 offset:4096
	ds_read_b128 v[202:205], v149 offset:5120
	ds_read_b128 v[206:209], v149 offset:6144
	ds_read_b128 v[210:213], v149 offset:7168
	s_waitcnt vmcnt(8)
	s_waitcnt lgkmcnt(0)
	s_barrier
	s_setprio 1
	v_mfma_f32_16x16x32_bf16 v[124:127], v[150:153], v[182:185], v[124:127]
	v_mfma_f32_16x16x32_bf16 v[120:123], v[158:161], v[182:185], v[120:123]
	v_mfma_f32_16x16x32_bf16 v[108:111], v[150:153], v[190:193], v[108:111]
	v_mfma_f32_16x16x32_bf16 v[104:107], v[158:161], v[190:193], v[104:107]
	v_mfma_f32_16x16x32_bf16 v[92:95], v[150:153], v[198:201], v[92:95]
	v_mfma_f32_16x16x32_bf16 v[88:91], v[158:161], v[198:201], v[88:91]
	v_mfma_f32_16x16x32_bf16 v[76:79], v[150:153], v[206:209], v[76:79]
	v_mfma_f32_16x16x32_bf16 v[72:75], v[158:161], v[206:209], v[72:75]
	v_mfma_f32_16x16x32_bf16 v[124:127], v[154:157], v[186:189], v[124:127]
	v_mfma_f32_16x16x32_bf16 v[120:123], v[162:165], v[186:189], v[120:123]
	v_mfma_f32_16x16x32_bf16 v[108:111], v[154:157], v[194:197], v[108:111]
	v_mfma_f32_16x16x32_bf16 v[104:107], v[162:165], v[194:197], v[104:107]
	v_mfma_f32_16x16x32_bf16 v[92:95], v[154:157], v[202:205], v[92:95]
	v_mfma_f32_16x16x32_bf16 v[88:91], v[162:165], v[202:205], v[88:91]
	v_mfma_f32_16x16x32_bf16 v[76:79], v[154:157], v[210:213], v[76:79]
	v_mfma_f32_16x16x32_bf16 v[72:75], v[162:165], v[210:213], v[72:75]
	s_setprio 0
	s_setprio 1
	v_mfma_f32_16x16x32_bf16 v[116:119], v[166:169], v[182:185], v[116:119]
	v_mfma_f32_16x16x32_bf16 v[112:115], v[174:177], v[182:185], v[112:115]
	v_mfma_f32_16x16x32_bf16 v[100:103], v[166:169], v[190:193], v[100:103]
	v_mfma_f32_16x16x32_bf16 v[96:99], v[174:177], v[190:193], v[96:99]
	v_mfma_f32_16x16x32_bf16 v[84:87], v[166:169], v[198:201], v[84:87]
	v_mfma_f32_16x16x32_bf16 v[80:83], v[174:177], v[198:201], v[80:83]
	v_mfma_f32_16x16x32_bf16 v[68:71], v[166:169], v[206:209], v[68:71]
	v_mfma_f32_16x16x32_bf16 v[64:67], v[174:177], v[206:209], v[64:67]
	v_mfma_f32_16x16x32_bf16 v[116:119], v[170:173], v[186:189], v[116:119]
	v_mfma_f32_16x16x32_bf16 v[112:115], v[178:181], v[186:189], v[112:115]
	v_mfma_f32_16x16x32_bf16 v[100:103], v[170:173], v[194:197], v[100:103]
	v_mfma_f32_16x16x32_bf16 v[96:99], v[178:181], v[194:197], v[96:99]
	v_mfma_f32_16x16x32_bf16 v[84:87], v[170:173], v[202:205], v[84:87]
	v_mfma_f32_16x16x32_bf16 v[80:83], v[178:181], v[202:205], v[80:83]
	v_mfma_f32_16x16x32_bf16 v[68:71], v[170:173], v[210:213], v[68:71]
	v_mfma_f32_16x16x32_bf16 v[64:67], v[178:181], v[210:213], v[64:67]
	s_setprio 0
	s_barrier
	s_add_u32 s98, s26, s10
	s_addc_u32 s99, s27, s11
	s_add_u32 s100, s28, s10
	s_addc_u32 s101, s29, s11
	s_mov_b32 m0, s23
	ds_read_b128 v[194:197], v149 offset:19456
	global_load_lds_dwordx4 v134, s[28:29]
	s_mov_b32 m0, s37
	ds_read_b128 v[198:201], v149 offset:20480
	global_load_lds_dwordx4 v130, s[28:29]
	s_add_i32 s57, s48, s34
	s_mov_b32 m0, s57
	ds_read_b128 v[182:185], v149 offset:16384
	global_load_lds_dwordx4 v132, s[26:27]
	s_add_i32 m0, s57, 0x2000
	s_add_u32 s60, s26, 0x40000
	s_addc_u32 s61, s27, 0
	s_add_i32 s57, s49, s34
	global_load_lds_dwordx4 v128, s[26:27]
	s_mov_b32 m0, s57
	ds_read_b128 v[186:189], v149 offset:17408
	global_load_lds_dwordx4 v132, s[60:61]
	s_add_i32 m0, s57, 0x2000
	ds_read_b128 v[190:193], v149 offset:18432
	global_load_lds_dwordx4 v128, s[60:61]
	ds_read_b128 v[202:205], v149 offset:21504
	ds_read_b128 v[206:209], v149 offset:22528
	ds_read_b128 v[210:213], v149 offset:23552
	s_waitcnt vmcnt(8)
	s_waitcnt lgkmcnt(0)
	s_barrier
	s_setprio 1
	v_mfma_f32_16x16x32_bf16 v[60:63], v[150:153], v[182:185], v[60:63]
	v_mfma_f32_16x16x32_bf16 v[56:59], v[158:161], v[182:185], v[56:59]
	v_mfma_f32_16x16x32_bf16 v[44:47], v[150:153], v[190:193], v[44:47]
	v_mfma_f32_16x16x32_bf16 v[40:43], v[158:161], v[190:193], v[40:43]
	v_mfma_f32_16x16x32_bf16 v[28:31], v[150:153], v[198:201], v[28:31]
	v_mfma_f32_16x16x32_bf16 v[24:27], v[158:161], v[198:201], v[24:27]
	v_mfma_f32_16x16x32_bf16 v[12:15], v[150:153], v[206:209], v[12:15]
	v_mfma_f32_16x16x32_bf16 v[8:11], v[158:161], v[206:209], v[8:11]
	v_mfma_f32_16x16x32_bf16 v[60:63], v[154:157], v[186:189], v[60:63]
	v_mfma_f32_16x16x32_bf16 v[56:59], v[162:165], v[186:189], v[56:59]
	v_mfma_f32_16x16x32_bf16 v[44:47], v[154:157], v[194:197], v[44:47]
	v_mfma_f32_16x16x32_bf16 v[40:43], v[162:165], v[194:197], v[40:43]
	v_mfma_f32_16x16x32_bf16 v[28:31], v[154:157], v[202:205], v[28:31]
	v_mfma_f32_16x16x32_bf16 v[24:27], v[162:165], v[202:205], v[24:27]
	v_mfma_f32_16x16x32_bf16 v[12:15], v[154:157], v[210:213], v[12:15]
	v_mfma_f32_16x16x32_bf16 v[8:11], v[162:165], v[210:213], v[8:11]
	s_setprio 0
	s_setprio 1
	v_mfma_f32_16x16x32_bf16 v[52:55], v[166:169], v[182:185], v[52:55]
	v_mfma_f32_16x16x32_bf16 v[48:51], v[174:177], v[182:185], v[48:51]
	v_mfma_f32_16x16x32_bf16 v[36:39], v[166:169], v[190:193], v[36:39]
	v_mfma_f32_16x16x32_bf16 v[32:35], v[174:177], v[190:193], v[32:35]
	v_mfma_f32_16x16x32_bf16 v[20:23], v[166:169], v[198:201], v[20:23]
	v_mfma_f32_16x16x32_bf16 v[16:19], v[174:177], v[198:201], v[16:19]
	v_mfma_f32_16x16x32_bf16 v[4:7], v[166:169], v[206:209], v[4:7]
	v_mfma_f32_16x16x32_bf16 v[0:3], v[174:177], v[206:209], v[0:3]
	v_mfma_f32_16x16x32_bf16 v[52:55], v[170:173], v[186:189], v[52:55]
	v_mfma_f32_16x16x32_bf16 v[48:51], v[178:181], v[186:189], v[48:51]
	v_mfma_f32_16x16x32_bf16 v[36:39], v[170:173], v[194:197], v[36:39]
	v_mfma_f32_16x16x32_bf16 v[32:35], v[178:181], v[194:197], v[32:35]
	v_mfma_f32_16x16x32_bf16 v[20:23], v[170:173], v[202:205], v[20:23]
	v_mfma_f32_16x16x32_bf16 v[16:19], v[178:181], v[202:205], v[16:19]
	v_mfma_f32_16x16x32_bf16 v[4:7], v[170:173], v[210:213], v[4:7]
	v_mfma_f32_16x16x32_bf16 v[0:3], v[178:181], v[210:213], v[0:3]
	s_setprio 0
	s_barrier
; #define PG8_STAGE(bufoff, gbase, voff) do { _Pragma("unroll") for (int _i = 0; _i < 2; ++_i) \
;         __builtin_amdgcn_global_load_lds((const unsigned*)((const char*)(gbase) + (voff)[_i]), (PG8_LAS unsigned*)(lds + (bufoff) + ldsw + _i * 8192), 16, 0, 0); } while (0)
; #define PG8_LDA(dst, b, h) do { _Pragma("unroll") for (int m = 0; m < 4; ++m) _Pragma("unroll") for (int k = 0; k < 2; ++k) dst[m][k] = *(const PG8_LAS bf16x8*)(lds + PG8_SA(b, h) + aoff + m * 2048 + k * 1024); } while (0)
; #define PG8_LDB(dst, b, h) do { _Pragma("unroll") for (int n = 0; n < 2; ++n) _Pragma("unroll") for (int k = 0; k < 2; ++k) dst[n][k] = *(const PG8_LAS bf16x8*)(lds + PG8_SB(b, h) + boff + n * 2048 + k * 1024); } while (0)
; #define PG8_MMA(ai, bj, At, Bt) do { __builtin_amdgcn_s_setprio(1); _Pragma("unroll") for (int m = 0; m < 4; ++m) _Pragma("unroll") for (int n = 0; n < 2; ++n) _Pragma("unroll") for (int k = 0; k < 2; ++k) \
;         acc[ai][bj][m][n] = __builtin_amdgcn_mfma_f32_16x16x32_bf16(Bt[n][k], At[m][k], acc[ai][bj][m][n], 0, 0, 0); __builtin_amdgcn_s_setprio(0); } while (0)
; #define PG8_WAIT_V(n) asm volatile("s_waitcnt vmcnt(" #n ")" ::: "memory")
; #define PG8_WAIT_L(n) asm volatile("s_waitcnt lgkmcnt(" #n ")" ::: "memory")
; #define PG8_BAR __builtin_amdgcn_s_barrier()
; #define PG8_SCHED __builtin_amdgcn_sched_barrier(0)
; template <class Epi, class Sched, bool ALIGN_EPI = false, bool SP2 = false>
; __device__ __forceinline__ void gemm_phase(PG8_LAS unsigned char* lds, const Gemm g, const Sched& S, const Epi& E, int tid_in) {
;     ...
;             PG8_LDB(B0, 1, 0); PG8_LDB(B1, 1, 1); PG8_SCHED; PG8_LDA(At, 1, 0); PG8_STAGE(PG8_SA(0, 1), a2 + hstep, voffA);
;             PG8_WAIT_V(8); PG8_WAIT_L(0); PG8_BAR; PG8_MMA(0, 0, At, B0); PG8_MMA(0, 1, At, B1); PG8_BAR; PG8_SCHED;
;             PG8_LDA(At, 1, 1); PG8_STAGE(PG8_SB(1, 0), b3, voffB); PG8_STAGE(PG8_SB(1, 1), b3 + hstep, voffB); PG8_STAGE(PG8_SA(1, 0), a3, voffA);
;             PG8_WAIT_V(8); PG8_WAIT_L(0); PG8_BAR; PG8_MMA(1, 0, At, B0); PG8_MMA(1, 1, At, B1); PG8_BAR; PG8_SCHED;
	s_add_i32 s57, 0, 0x18000
	s_add_i32 s59, 0, 0x1c000
	s_add_u32 s28, s28, 0x40000
	s_addc_u32 s29, s29, 0
	s_mov_b32 m0, s38
	s_nop 0
	global_load_lds_dwordx4 v134, s[28:29]
	s_mov_b32 m0, s39
	s_nop 0
	global_load_lds_dwordx4 v130, s[28:29]
	v_add_u32_e32 v162, s57, v145
	v_add_u32_e32 v178, s59, v145
	ds_read_b128 v[150:153], v162
	ds_read_b128 v[154:157], v162 offset:1024
	ds_read_b128 v[158:161], v162 offset:2048
	ds_read_b128 v[162:165], v162 offset:3072
	ds_read_b128 v[166:169], v178
	ds_read_b128 v[170:173], v178 offset:1024
	ds_read_b128 v[174:177], v178 offset:2048
	ds_read_b128 v[178:181], v178 offset:3072
	ds_read_b128 v[182:185], v149 offset:32768
	ds_read_b128 v[186:189], v149 offset:33792
	ds_read_b128 v[190:193], v149 offset:34816
	ds_read_b128 v[194:197], v149 offset:35840
	ds_read_b128 v[198:201], v149 offset:36864
	ds_read_b128 v[202:205], v149 offset:37888
	ds_read_b128 v[206:209], v149 offset:38912
	ds_read_b128 v[210:213], v149 offset:39936
	s_waitcnt vmcnt(8)
	s_waitcnt lgkmcnt(0)
	s_barrier
	s_setprio 1
	v_mfma_f32_16x16x32_bf16 v[124:127], v[150:153], v[182:185], v[124:127]
	v_mfma_f32_16x16x32_bf16 v[120:123], v[158:161], v[182:185], v[120:123]
	v_mfma_f32_16x16x32_bf16 v[108:111], v[150:153], v[190:193], v[108:111]
	v_mfma_f32_16x16x32_bf16 v[104:107], v[158:161], v[190:193], v[104:107]
	v_mfma_f32_16x16x32_bf16 v[92:95], v[150:153], v[198:201], v[92:95]
	v_mfma_f32_16x16x32_bf16 v[88:91], v[158:161], v[198:201], v[88:91]
	v_mfma_f32_16x16x32_bf16 v[76:79], v[150:153], v[206:209], v[76:79]
	v_mfma_f32_16x16x32_bf16 v[72:75], v[158:161], v[206:209], v[72:75]
	v_mfma_f32_16x16x32_bf16 v[124:127], v[154:157], v[186:189], v[124:127]
	v_mfma_f32_16x16x32_bf16 v[120:123], v[162:165], v[186:189], v[120:123]
	v_mfma_f32_16x16x32_bf16 v[108:111], v[154:157], v[194:197], v[108:111]
	v_mfma_f32_16x16x32_bf16 v[104:107], v[162:165], v[194:197], v[104:107]
	v_mfma_f32_16x16x32_bf16 v[92:95], v[154:157], v[202:205], v[92:95]
	v_mfma_f32_16x16x32_bf16 v[88:91], v[162:165], v[202:205], v[88:91]
	v_mfma_f32_16x16x32_bf16 v[76:79], v[154:157], v[210:213], v[76:79]
	v_mfma_f32_16x16x32_bf16 v[72:75], v[162:165], v[210:213], v[72:75]
	s_setprio 0
	s_setprio 1
	v_mfma_f32_16x16x32_bf16 v[116:119], v[166:169], v[182:185], v[116:119]
	v_mfma_f32_16x16x32_bf16 v[112:115], v[174:177], v[182:185], v[112:115]
	v_mfma_f32_16x16x32_bf16 v[100:103], v[166:169], v[190:193], v[100:103]
	v_mfma_f32_16x16x32_bf16 v[96:99], v[174:177], v[190:193], v[96:99]
	v_mfma_f32_16x16x32_bf16 v[84:87], v[166:169], v[198:201], v[84:87]
	v_mfma_f32_16x16x32_bf16 v[80:83], v[174:177], v[198:201], v[80:83]
	v_mfma_f32_16x16x32_bf16 v[68:71], v[166:169], v[206:209], v[68:71]
	v_mfma_f32_16x16x32_bf16 v[64:67], v[174:177], v[206:209], v[64:67]
	v_mfma_f32_16x16x32_bf16 v[116:119], v[170:173], v[186:189], v[116:119]
	v_mfma_f32_16x16x32_bf16 v[112:115], v[178:181], v[186:189], v[112:115]
	v_mfma_f32_16x16x32_bf16 v[100:103], v[170:173], v[194:197], v[100:103]
	v_mfma_f32_16x16x32_bf16 v[96:99], v[178:181], v[194:197], v[96:99]
	v_mfma_f32_16x16x32_bf16 v[84:87], v[170:173], v[202:205], v[84:87]
	v_mfma_f32_16x16x32_bf16 v[80:83], v[178:181], v[202:205], v[80:83]
	v_mfma_f32_16x16x32_bf16 v[68:71], v[170:173], v[210:213], v[68:71]
	v_mfma_f32_16x16x32_bf16 v[64:67], v[178:181], v[210:213], v[64:67]
	s_setprio 0
	s_barrier
	s_mov_b32 m0, s44
	ds_read_b128 v[194:197], v149 offset:52224
	global_load_lds_dwordx4 v134, s[100:101]
	s_mov_b32 m0, s45
	ds_read_b128 v[198:201], v149 offset:53248
	global_load_lds_dwordx4 v130, s[100:101]
	s_add_i32 s28, s57, s34
	s_mov_b32 m0, s28
	ds_read_b128 v[182:185], v149 offset:49152
	global_load_lds_dwordx4 v132, s[98:99]
	s_add_i32 m0, s28, 0x2000
	s_add_u32 s26, s26, 0x40080
	s_addc_u32 s27, s27, 0
	s_add_i32 s28, s59, s34
	global_load_lds_dwordx4 v128, s[98:99]
	s_mov_b32 m0, s28
	ds_read_b128 v[186:189], v149 offset:50176
	global_load_lds_dwordx4 v132, s[26:27]
	s_add_i32 m0, s28, 0x2000
	ds_read_b128 v[190:193], v149 offset:51200
	global_load_lds_dwordx4 v128, s[26:27]
	ds_read_b128 v[202:205], v149 offset:54272
	ds_read_b128 v[206:209], v149 offset:55296
	ds_read_b128 v[210:213], v149 offset:56320
	s_waitcnt vmcnt(8)
	s_waitcnt lgkmcnt(0)
	s_barrier
	s_setprio 1
	v_mfma_f32_16x16x32_bf16 v[60:63], v[150:153], v[182:185], v[60:63]
	v_mfma_f32_16x16x32_bf16 v[56:59], v[158:161], v[182:185], v[56:59]
	v_mfma_f32_16x16x32_bf16 v[44:47], v[150:153], v[190:193], v[44:47]
	v_mfma_f32_16x16x32_bf16 v[40:43], v[158:161], v[190:193], v[40:43]
	v_mfma_f32_16x16x32_bf16 v[28:31], v[150:153], v[198:201], v[28:31]
	v_mfma_f32_16x16x32_bf16 v[24:27], v[158:161], v[198:201], v[24:27]
	v_mfma_f32_16x16x32_bf16 v[12:15], v[150:153], v[206:209], v[12:15]
	v_mfma_f32_16x16x32_bf16 v[8:11], v[158:161], v[206:209], v[8:11]
	v_mfma_f32_16x16x32_bf16 v[60:63], v[154:157], v[186:189], v[60:63]
	v_mfma_f32_16x16x32_bf16 v[56:59], v[162:165], v[186:189], v[56:59]
	v_mfma_f32_16x16x32_bf16 v[44:47], v[154:157], v[194:197], v[44:47]
	v_mfma_f32_16x16x32_bf16 v[40:43], v[162:165], v[194:197], v[40:43]
	v_mfma_f32_16x16x32_bf16 v[28:31], v[154:157], v[202:205], v[28:31]
	v_mfma_f32_16x16x32_bf16 v[24:27], v[162:165], v[202:205], v[24:27]
	v_mfma_f32_16x16x32_bf16 v[12:15], v[154:157], v[210:213], v[12:15]
	v_mfma_f32_16x16x32_bf16 v[8:11], v[162:165], v[210:213], v[8:11]
	s_setprio 0
	s_setprio 1
	v_mfma_f32_16x16x32_bf16 v[52:55], v[166:169], v[182:185], v[52:55]
	v_mfma_f32_16x16x32_bf16 v[48:51], v[174:177], v[182:185], v[48:51]
	v_mfma_f32_16x16x32_bf16 v[36:39], v[166:169], v[190:193], v[36:39]
	v_mfma_f32_16x16x32_bf16 v[32:35], v[174:177], v[190:193], v[32:35]
	v_mfma_f32_16x16x32_bf16 v[20:23], v[166:169], v[198:201], v[20:23]
	v_mfma_f32_16x16x32_bf16 v[16:19], v[174:177], v[198:201], v[16:19]
	v_mfma_f32_16x16x32_bf16 v[4:7], v[166:169], v[206:209], v[4:7]
	v_mfma_f32_16x16x32_bf16 v[0:3], v[174:177], v[206:209], v[0:3]
	v_mfma_f32_16x16x32_bf16 v[52:55], v[170:173], v[186:189], v[52:55]
	v_mfma_f32_16x16x32_bf16 v[48:51], v[178:181], v[186:189], v[48:51]
	v_mfma_f32_16x16x32_bf16 v[36:39], v[170:173], v[194:197], v[36:39]
	v_mfma_f32_16x16x32_bf16 v[32:35], v[178:181], v[194:197], v[32:35]
	v_mfma_f32_16x16x32_bf16 v[20:23], v[170:173], v[202:205], v[20:23]
	v_mfma_f32_16x16x32_bf16 v[16:19], v[178:181], v[202:205], v[16:19]
	v_mfma_f32_16x16x32_bf16 v[4:7], v[170:173], v[210:213], v[4:7]
	v_mfma_f32_16x16x32_bf16 v[0:3], v[178:181], v[210:213], v[0:3]
	s_setprio 0
	s_barrier
	s_add_i32 s56, s56, 2
	s_add_u32 s24, s24, 0x100
	s_addc_u32 s25, s25, 0
	s_add_u32 s54, s54, 0x100
	s_addc_u32 s55, s55, 0
	s_cmp_gt_u32 s56, 13
	s_cbranch_scc0 .LBB0_376
	s_and_b64 vcc, exec, s[12:13]
	s_cbranch_vccz .LBB0_379
	s_barrier

; #define PG8_STAGE(bufoff, gbase, voff) do { _Pragma("unroll") for (int _i = 0; _i < 2; ++_i) \
;         __builtin_amdgcn_global_load_lds((const unsigned*)((const char*)(gbase) + (voff)[_i]), (PG8_LAS unsigned*)(lds + (bufoff) + ldsw + _i * 8192), 16, 0, 0); } while (0)
; #define PG8_LDA(dst, b, h) do { _Pragma("unroll") for (int m = 0; m < 4; ++m) _Pragma("unroll") for (int k = 0; k < 2; ++k) dst[m][k] = *(const PG8_LAS bf16x8*)(lds + PG8_SA(b, h) + aoff + m * 2048 + k * 1024); } while (0)
; #define PG8_LDB(dst, b, h) do { _Pragma("unroll") for (int n = 0; n < 2; ++n) _Pragma("unroll") for (int k = 0; k < 2; ++k) dst[n][k] = *(const PG8_LAS bf16x8*)(lds + PG8_SB(b, h) + boff + n * 2048 + k * 1024); } while (0)
; #define PG8_MMA(ai, bj, At, Bt) do { __builtin_amdgcn_s_setprio(1); _Pragma("unroll") for (int m = 0; m < 4; ++m) _Pragma("unroll") for (int n = 0; n < 2; ++n) _Pragma("unroll") for (int k = 0; k < 2; ++k) \
;         acc[ai][bj][m][n] = __builtin_amdgcn_mfma_f32_16x16x32_bf16(Bt[n][k], At[m][k], acc[ai][bj][m][n], 0, 0, 0); __builtin_amdgcn_s_setprio(0); } while (0)
; #define PG8_WAIT_V(n) asm volatile("s_waitcnt vmcnt(" #n ")" ::: "memory")
; #define PG8_WAIT_L(n) asm volatile("s_waitcnt lgkmcnt(" #n ")" ::: "memory")
; template <class Epi, class Sched, bool ALIGN_EPI = false, bool SP2 = false>
; __device__ __forceinline__ void gemm_phase(PG8_LAS unsigned char* lds, const Gemm g, const Sched& S, const Epi& E, int tid_in) {
;     ...
;             const bool last = (t == nt - 2);
;             const char* a1 = cA + (size_t)(t + 1) * kstep;
;             const char* a2 = last ? nA : cA + (size_t)(t + 2) * kstep; const char* b2 = last ? nB : cB + (size_t)(t + 2) * kstep;
;             const char* a3 = a2 + kstep; const char* b3 = b2 + kstep;
;             if (last && has_next) S.a_ready(nxt);
;             if constexpr (SP2) {
;             PG8_LDB(B0, 0, 0); PG8_LDB(B1, 0, 1); PG8_SCHED; PG8_LDA(At, 0, 0); PG8_STAGE(PG8_SA(1, 1), a1 + hstep, voffA);
;             PG8_WAIT_V(8); PG8_WAIT_L(0); PG8_BAR; PG8_MMA(0, 0, At, B0); PG8_MMA(0, 1, At, B1); PG8_BAR; PG8_SCHED;
;             PG8_LDA(At, 0, 1); PG8_STAGE(PG8_SB(0, 0), b2, voffB); PG8_STAGE(PG8_SB(0, 1), b2 + hstep, voffB); PG8_STAGE(PG8_SA(0, 0), a2, voffA);
;             PG8_WAIT_V(8); PG8_WAIT_L(0); PG8_BAR; PG8_MMA(1, 0, At, B0); PG8_MMA(1, 1, At, B1); PG8_BAR; PG8_SCHED;
.LBB0_461:
	s_add_u32 s6, s48, 0x100
	s_addc_u32 s7, s49, 0
	s_cmp_eq_u32 s76, 40
	s_cselect_b32 s53, s45, s7
	s_cselect_b32 s52, s44, s6
	s_cselect_b32 s51, s47, s75
	s_cselect_b32 s50, s46, s12
	s_add_i32 m0, s60, 0xc000
	ds_read_b128 v[128:131], v236
	global_load_lds_dwordx4 v200, s[48:49]
	s_add_i32 m0, s60, 0xe000
	ds_read_b128 v[132:135], v236 offset:1024
	global_load_lds_dwordx4 v202, s[48:49]
	ds_read_b128 v[136:139], v236 offset:2048
	ds_read_b128 v[140:143], v236 offset:3072
	ds_read_b128 v[144:147], v237
	ds_read_b128 v[148:151], v237 offset:1024
	ds_read_b128 v[152:155], v237 offset:2048
	ds_read_b128 v[156:159], v237 offset:3072
	ds_read_b128 v[160:163], v238
	ds_read_b128 v[164:167], v238 offset:1024
	ds_read_b128 v[168:171], v238 offset:2048
	ds_read_b128 v[172:175], v238 offset:3072
	ds_read_b128 v[176:179], v238 offset:4096
	ds_read_b128 v[180:183], v238 offset:5120
	ds_read_b128 v[184:187], v238 offset:6144
	ds_read_b128 v[188:191], v238 offset:7168
	s_waitcnt vmcnt(8)
	s_waitcnt lgkmcnt(0)
	s_barrier
	s_setprio 1
	v_mfma_f32_16x16x32_bf16 v[124:127], v[128:131], v[160:163], v[124:127]
	v_mfma_f32_16x16x32_bf16 v[120:123], v[136:139], v[160:163], v[120:123]
	v_mfma_f32_16x16x32_bf16 v[108:111], v[128:131], v[168:171], v[108:111]
	v_mfma_f32_16x16x32_bf16 v[104:107], v[136:139], v[168:171], v[104:107]
	v_mfma_f32_16x16x32_bf16 v[92:95], v[128:131], v[176:179], v[92:95]
	v_mfma_f32_16x16x32_bf16 v[88:91], v[136:139], v[176:179], v[88:91]
	v_mfma_f32_16x16x32_bf16 v[76:79], v[128:131], v[184:187], v[76:79]
	v_mfma_f32_16x16x32_bf16 v[72:75], v[136:139], v[184:187], v[72:75]
	v_mfma_f32_16x16x32_bf16 v[124:127], v[132:135], v[164:167], v[124:127]
	v_mfma_f32_16x16x32_bf16 v[120:123], v[140:143], v[164:167], v[120:123]
	v_mfma_f32_16x16x32_bf16 v[108:111], v[132:135], v[172:175], v[108:111]
	v_mfma_f32_16x16x32_bf16 v[104:107], v[140:143], v[172:175], v[104:107]
	v_mfma_f32_16x16x32_bf16 v[92:95], v[132:135], v[180:183], v[92:95]
	v_mfma_f32_16x16x32_bf16 v[88:91], v[140:143], v[180:183], v[88:91]
	v_mfma_f32_16x16x32_bf16 v[76:79], v[132:135], v[188:191], v[76:79]
	v_mfma_f32_16x16x32_bf16 v[72:75], v[140:143], v[188:191], v[72:75]
	s_setprio 0
	s_setprio 1
	v_mfma_f32_16x16x32_bf16 v[116:119], v[144:147], v[160:163], v[116:119]
	v_mfma_f32_16x16x32_bf16 v[112:115], v[152:155], v[160:163], v[112:115]
	v_mfma_f32_16x16x32_bf16 v[100:103], v[144:147], v[168:171], v[100:103]
	v_mfma_f32_16x16x32_bf16 v[96:99], v[152:155], v[168:171], v[96:99]
	v_mfma_f32_16x16x32_bf16 v[84:87], v[144:147], v[176:179], v[84:87]
	v_mfma_f32_16x16x32_bf16 v[80:83], v[152:155], v[176:179], v[80:83]
	v_mfma_f32_16x16x32_bf16 v[68:71], v[144:147], v[184:187], v[68:71]
	v_mfma_f32_16x16x32_bf16 v[64:67], v[152:155], v[184:187], v[64:67]
	v_mfma_f32_16x16x32_bf16 v[116:119], v[148:151], v[164:167], v[116:119]
	v_mfma_f32_16x16x32_bf16 v[112:115], v[156:159], v[164:167], v[112:115]
	v_mfma_f32_16x16x32_bf16 v[100:103], v[148:151], v[172:175], v[100:103]
	v_mfma_f32_16x16x32_bf16 v[96:99], v[156:159], v[172:175], v[96:99]
	v_mfma_f32_16x16x32_bf16 v[84:87], v[148:151], v[180:183], v[84:87]
	v_mfma_f32_16x16x32_bf16 v[80:83], v[156:159], v[180:183], v[80:83]
	v_mfma_f32_16x16x32_bf16 v[68:71], v[148:151], v[188:191], v[68:71]
	v_mfma_f32_16x16x32_bf16 v[64:67], v[156:159], v[188:191], v[64:67]
	s_setprio 0
	s_barrier
	s_add_u32 s98, s50, s22
	s_addc_u32 s99, s51, s23
	s_add_u32 s100, s52, s22
	s_addc_u32 s101, s53, s23
	s_mov_b32 m0, s60
	ds_read_b128 v[172:175], v238 offset:19456
	global_load_lds_dwordx4 v192, s[52:53]
	s_mov_b32 m0, s61
	ds_read_b128 v[176:179], v238 offset:20480
	global_load_lds_dwordx4 v196, s[52:53]
	s_add_i32 s48, s70, s59
	s_mov_b32 m0, s48
	ds_read_b128 v[160:163], v238 offset:16384
	global_load_lds_dwordx4 v194, s[50:51]
	s_add_i32 m0, s48, 0x2000
	s_add_u32 s48, s50, 0xb0000
	s_addc_u32 s49, s51, 0
	s_add_i32 s77, s71, s59
	global_load_lds_dwordx4 v198, s[50:51]
	s_mov_b32 m0, s77
	ds_read_b128 v[164:167], v238 offset:17408
	global_load_lds_dwordx4 v194, s[48:49]
	s_add_i32 m0, s77, 0x2000
	ds_read_b128 v[168:171], v238 offset:18432
	global_load_lds_dwordx4 v198, s[48:49]
	ds_read_b128 v[180:183], v238 offset:21504
	ds_read_b128 v[184:187], v238 offset:22528
	ds_read_b128 v[188:191], v238 offset:23552
	s_waitcnt vmcnt(8)
	s_waitcnt lgkmcnt(0)
	s_barrier
	s_setprio 1
	v_mfma_f32_16x16x32_bf16 v[60:63], v[128:131], v[160:163], v[60:63]
	v_mfma_f32_16x16x32_bf16 v[56:59], v[136:139], v[160:163], v[56:59]
	v_mfma_f32_16x16x32_bf16 v[44:47], v[128:131], v[168:171], v[44:47]
	v_mfma_f32_16x16x32_bf16 v[40:43], v[136:139], v[168:171], v[40:43]
	v_mfma_f32_16x16x32_bf16 v[28:31], v[128:131], v[176:179], v[28:31]
	v_mfma_f32_16x16x32_bf16 v[24:27], v[136:139], v[176:179], v[24:27]
	v_mfma_f32_16x16x32_bf16 v[12:15], v[128:131], v[184:187], v[12:15]
	v_mfma_f32_16x16x32_bf16 v[8:11], v[136:139], v[184:187], v[8:11]
	v_mfma_f32_16x16x32_bf16 v[60:63], v[132:135], v[164:167], v[60:63]
	v_mfma_f32_16x16x32_bf16 v[56:59], v[140:143], v[164:167], v[56:59]
	v_mfma_f32_16x16x32_bf16 v[44:47], v[132:135], v[172:175], v[44:47]
	v_mfma_f32_16x16x32_bf16 v[40:43], v[140:143], v[172:175], v[40:43]
	v_mfma_f32_16x16x32_bf16 v[28:31], v[132:135], v[180:183], v[28:31]
	v_mfma_f32_16x16x32_bf16 v[24:27], v[140:143], v[180:183], v[24:27]
	v_mfma_f32_16x16x32_bf16 v[12:15], v[132:135], v[188:191], v[12:15]
	v_mfma_f32_16x16x32_bf16 v[8:11], v[140:143], v[188:191], v[8:11]
	s_setprio 0
	s_setprio 1
	v_mfma_f32_16x16x32_bf16 v[52:55], v[144:147], v[160:163], v[52:55]
	v_mfma_f32_16x16x32_bf16 v[48:51], v[152:155], v[160:163], v[48:51]
	v_mfma_f32_16x16x32_bf16 v[36:39], v[144:147], v[168:171], v[36:39]
	v_mfma_f32_16x16x32_bf16 v[32:35], v[152:155], v[168:171], v[32:35]
	v_mfma_f32_16x16x32_bf16 v[20:23], v[144:147], v[176:179], v[20:23]
	v_mfma_f32_16x16x32_bf16 v[16:19], v[152:155], v[176:179], v[16:19]
	v_mfma_f32_16x16x32_bf16 v[4:7], v[144:147], v[184:187], v[4:7]
	v_mfma_f32_16x16x32_bf16 v[0:3], v[152:155], v[184:187], v[0:3]
	v_mfma_f32_16x16x32_bf16 v[52:55], v[148:151], v[164:167], v[52:55]
	v_mfma_f32_16x16x32_bf16 v[48:51], v[156:159], v[164:167], v[48:51]
	v_mfma_f32_16x16x32_bf16 v[36:39], v[148:151], v[172:175], v[36:39]
	v_mfma_f32_16x16x32_bf16 v[32:35], v[156:159], v[172:175], v[32:35]
	v_mfma_f32_16x16x32_bf16 v[20:23], v[148:151], v[180:183], v[20:23]
	v_mfma_f32_16x16x32_bf16 v[16:19], v[156:159], v[180:183], v[16:19]
	v_mfma_f32_16x16x32_bf16 v[4:7], v[148:151], v[188:191], v[4:7]
	v_mfma_f32_16x16x32_bf16 v[0:3], v[156:159], v[188:191], v[0:3]
	s_setprio 0
	s_barrier
; #define PG8_STAGE(bufoff, gbase, voff) do { _Pragma("unroll") for (int _i = 0; _i < 2; ++_i) \
;         __builtin_amdgcn_global_load_lds((const unsigned*)((const char*)(gbase) + (voff)[_i]), (PG8_LAS unsigned*)(lds + (bufoff) + ldsw + _i * 8192), 16, 0, 0); } while (0)
; #define PG8_LDA(dst, b, h) do { _Pragma("unroll") for (int m = 0; m < 4; ++m) _Pragma("unroll") for (int k = 0; k < 2; ++k) dst[m][k] = *(const PG8_LAS bf16x8*)(lds + PG8_SA(b, h) + aoff + m * 2048 + k * 1024); } while (0)
; #define PG8_LDB(dst, b, h) do { _Pragma("unroll") for (int n = 0; n < 2; ++n) _Pragma("unroll") for (int k = 0; k < 2; ++k) dst[n][k] = *(const PG8_LAS bf16x8*)(lds + PG8_SB(b, h) + boff + n * 2048 + k * 1024); } while (0)
; #define PG8_MMA(ai, bj, At, Bt) do { __builtin_amdgcn_s_setprio(1); _Pragma("unroll") for (int m = 0; m < 4; ++m) _Pragma("unroll") for (int n = 0; n < 2; ++n) _Pragma("unroll") for (int k = 0; k < 2; ++k) \
;         acc[ai][bj][m][n] = __builtin_amdgcn_mfma_f32_16x16x32_bf16(Bt[n][k], At[m][k], acc[ai][bj][m][n], 0, 0, 0); __builtin_amdgcn_s_setprio(0); } while (0)
; #define PG8_WAIT_V(n) asm volatile("s_waitcnt vmcnt(" #n ")" ::: "memory")
; #define PG8_WAIT_L(n) asm volatile("s_waitcnt lgkmcnt(" #n ")" ::: "memory")
; #define PG8_BAR __builtin_amdgcn_s_barrier()
; #define PG8_SCHED __builtin_amdgcn_sched_barrier(0)
; template <class Epi, class Sched, bool ALIGN_EPI = false, bool SP2 = false>
; __device__ __forceinline__ void gemm_phase(PG8_LAS unsigned char* lds, const Gemm g, const Sched& S, const Epi& E, int tid_in) {
;     ...
;             PG8_LDB(B0, 1, 0); PG8_LDB(B1, 1, 1); PG8_SCHED; PG8_LDA(At, 1, 0); PG8_STAGE(PG8_SA(0, 1), a2 + hstep, voffA);
;             PG8_WAIT_V(8); PG8_WAIT_L(0); PG8_BAR; PG8_MMA(0, 0, At, B0); PG8_MMA(0, 1, At, B1); PG8_BAR; PG8_SCHED;
;             PG8_LDA(At, 1, 1); PG8_STAGE(PG8_SB(1, 0), b3, voffB); PG8_STAGE(PG8_SB(1, 1), b3 + hstep, voffB); PG8_STAGE(PG8_SA(1, 0), a3, voffA);
;             PG8_WAIT_V(8); PG8_WAIT_L(0); PG8_BAR; PG8_MMA(1, 0, At, B0); PG8_MMA(1, 1, At, B1); PG8_BAR; PG8_SCHED;
	s_add_i32 s77, 0, 0x18000
	s_add_i32 s78, 0, 0x1c000
	s_add_u32 s48, s52, 0xb0000
	s_addc_u32 s49, s53, 0
	s_mov_b32 m0, s62
	s_nop 0
	global_load_lds_dwordx4 v192, s[48:49]
	s_mov_b32 m0, s63
	s_nop 0
	global_load_lds_dwordx4 v196, s[48:49]
	v_add_u32_e32 v140, s77, v232
	v_add_u32_e32 v156, s78, v232
	ds_read_b128 v[128:131], v140
	ds_read_b128 v[132:135], v140 offset:1024
	ds_read_b128 v[136:139], v140 offset:2048
	ds_read_b128 v[140:143], v140 offset:3072
	ds_read_b128 v[144:147], v156
	ds_read_b128 v[148:151], v156 offset:1024
	ds_read_b128 v[152:155], v156 offset:2048
	ds_read_b128 v[156:159], v156 offset:3072
	ds_read_b128 v[160:163], v238 offset:32768
	ds_read_b128 v[164:167], v238 offset:33792
	ds_read_b128 v[168:171], v238 offset:34816
	ds_read_b128 v[172:175], v238 offset:35840
	ds_read_b128 v[176:179], v238 offset:36864
	ds_read_b128 v[180:183], v238 offset:37888
	ds_read_b128 v[184:187], v238 offset:38912
	ds_read_b128 v[188:191], v238 offset:39936
	s_waitcnt vmcnt(8)
	s_waitcnt lgkmcnt(0)
	s_barrier
	s_setprio 1
	v_mfma_f32_16x16x32_bf16 v[124:127], v[128:131], v[160:163], v[124:127]
	v_mfma_f32_16x16x32_bf16 v[120:123], v[136:139], v[160:163], v[120:123]
	v_mfma_f32_16x16x32_bf16 v[108:111], v[128:131], v[168:171], v[108:111]
	v_mfma_f32_16x16x32_bf16 v[104:107], v[136:139], v[168:171], v[104:107]
	v_mfma_f32_16x16x32_bf16 v[92:95], v[128:131], v[176:179], v[92:95]
	v_mfma_f32_16x16x32_bf16 v[88:91], v[136:139], v[176:179], v[88:91]
	v_mfma_f32_16x16x32_bf16 v[76:79], v[128:131], v[184:187], v[76:79]
	v_mfma_f32_16x16x32_bf16 v[72:75], v[136:139], v[184:187], v[72:75]
	v_mfma_f32_16x16x32_bf16 v[124:127], v[132:135], v[164:167], v[124:127]
	v_mfma_f32_16x16x32_bf16 v[120:123], v[140:143], v[164:167], v[120:123]
	v_mfma_f32_16x16x32_bf16 v[108:111], v[132:135], v[172:175], v[108:111]
	v_mfma_f32_16x16x32_bf16 v[104:107], v[140:143], v[172:175], v[104:107]
	v_mfma_f32_16x16x32_bf16 v[92:95], v[132:135], v[180:183], v[92:95]
	v_mfma_f32_16x16x32_bf16 v[88:91], v[140:143], v[180:183], v[88:91]
	v_mfma_f32_16x16x32_bf16 v[76:79], v[132:135], v[188:191], v[76:79]
	v_mfma_f32_16x16x32_bf16 v[72:75], v[140:143], v[188:191], v[72:75]
	s_setprio 0
	s_setprio 1
	v_mfma_f32_16x16x32_bf16 v[116:119], v[144:147], v[160:163], v[116:119]
	v_mfma_f32_16x16x32_bf16 v[112:115], v[152:155], v[160:163], v[112:115]
	v_mfma_f32_16x16x32_bf16 v[100:103], v[144:147], v[168:171], v[100:103]
	v_mfma_f32_16x16x32_bf16 v[96:99], v[152:155], v[168:171], v[96:99]
	v_mfma_f32_16x16x32_bf16 v[84:87], v[144:147], v[176:179], v[84:87]
	v_mfma_f32_16x16x32_bf16 v[80:83], v[152:155], v[176:179], v[80:83]
	v_mfma_f32_16x16x32_bf16 v[68:71], v[144:147], v[184:187], v[68:71]
	v_mfma_f32_16x16x32_bf16 v[64:67], v[152:155], v[184:187], v[64:67]
	v_mfma_f32_16x16x32_bf16 v[116:119], v[148:151], v[164:167], v[116:119]
	v_mfma_f32_16x16x32_bf16 v[112:115], v[156:159], v[164:167], v[112:115]
	v_mfma_f32_16x16x32_bf16 v[100:103], v[148:151], v[172:175], v[100:103]
	v_mfma_f32_16x16x32_bf16 v[96:99], v[156:159], v[172:175], v[96:99]
	v_mfma_f32_16x16x32_bf16 v[84:87], v[148:151], v[180:183], v[84:87]
	v_mfma_f32_16x16x32_bf16 v[80:83], v[156:159], v[180:183], v[80:83]
	v_mfma_f32_16x16x32_bf16 v[68:71], v[148:151], v[188:191], v[68:71]
	v_mfma_f32_16x16x32_bf16 v[64:67], v[156:159], v[188:191], v[64:67]
	s_setprio 0
	s_barrier
	s_mov_b32 m0, s65
	ds_read_b128 v[172:175], v238 offset:52224
	global_load_lds_dwordx4 v192, s[100:101]
	s_mov_b32 m0, s67
	ds_read_b128 v[176:179], v238 offset:53248
	global_load_lds_dwordx4 v196, s[100:101]
	s_add_i32 s48, s77, s59
	s_mov_b32 m0, s48
	ds_read_b128 v[160:163], v238 offset:49152
	global_load_lds_dwordx4 v194, s[98:99]
	s_add_i32 m0, s48, 0x2000
	s_add_u32 s48, s50, 0xb0080
	s_addc_u32 s49, s51, 0
	s_add_i32 s50, s78, s59
	global_load_lds_dwordx4 v198, s[98:99]
	s_mov_b32 m0, s50
	ds_read_b128 v[164:167], v238 offset:50176
	global_load_lds_dwordx4 v194, s[48:49]
	s_add_i32 m0, s50, 0x2000
	ds_read_b128 v[168:171], v238 offset:51200
	global_load_lds_dwordx4 v198, s[48:49]
	ds_read_b128 v[180:183], v238 offset:54272
	ds_read_b128 v[184:187], v238 offset:55296
	ds_read_b128 v[188:191], v238 offset:56320
	s_waitcnt vmcnt(8)
	s_waitcnt lgkmcnt(0)
	s_barrier
	s_setprio 1
	v_mfma_f32_16x16x32_bf16 v[60:63], v[128:131], v[160:163], v[60:63]
	v_mfma_f32_16x16x32_bf16 v[56:59], v[136:139], v[160:163], v[56:59]
	v_mfma_f32_16x16x32_bf16 v[44:47], v[128:131], v[168:171], v[44:47]
	v_mfma_f32_16x16x32_bf16 v[40:43], v[136:139], v[168:171], v[40:43]
	v_mfma_f32_16x16x32_bf16 v[28:31], v[128:131], v[176:179], v[28:31]
	v_mfma_f32_16x16x32_bf16 v[24:27], v[136:139], v[176:179], v[24:27]
	v_mfma_f32_16x16x32_bf16 v[12:15], v[128:131], v[184:187], v[12:15]
	v_mfma_f32_16x16x32_bf16 v[8:11], v[136:139], v[184:187], v[8:11]
	v_mfma_f32_16x16x32_bf16 v[60:63], v[132:135], v[164:167], v[60:63]
	v_mfma_f32_16x16x32_bf16 v[56:59], v[140:143], v[164:167], v[56:59]
	v_mfma_f32_16x16x32_bf16 v[44:47], v[132:135], v[172:175], v[44:47]
	v_mfma_f32_16x16x32_bf16 v[40:43], v[140:143], v[172:175], v[40:43]
	v_mfma_f32_16x16x32_bf16 v[28:31], v[132:135], v[180:183], v[28:31]
	v_mfma_f32_16x16x32_bf16 v[24:27], v[140:143], v[180:183], v[24:27]
	v_mfma_f32_16x16x32_bf16 v[12:15], v[132:135], v[188:191], v[12:15]
	v_mfma_f32_16x16x32_bf16 v[8:11], v[140:143], v[188:191], v[8:11]
	s_setprio 0
	s_setprio 1
	v_mfma_f32_16x16x32_bf16 v[52:55], v[144:147], v[160:163], v[52:55]
	v_mfma_f32_16x16x32_bf16 v[48:51], v[152:155], v[160:163], v[48:51]
	v_mfma_f32_16x16x32_bf16 v[36:39], v[144:147], v[168:171], v[36:39]
	v_mfma_f32_16x16x32_bf16 v[32:35], v[152:155], v[168:171], v[32:35]
	v_mfma_f32_16x16x32_bf16 v[20:23], v[144:147], v[176:179], v[20:23]
	v_mfma_f32_16x16x32_bf16 v[16:19], v[152:155], v[176:179], v[16:19]
	v_mfma_f32_16x16x32_bf16 v[4:7], v[144:147], v[184:187], v[4:7]
	v_mfma_f32_16x16x32_bf16 v[0:3], v[152:155], v[184:187], v[0:3]
	v_mfma_f32_16x16x32_bf16 v[52:55], v[148:151], v[164:167], v[52:55]
	v_mfma_f32_16x16x32_bf16 v[48:51], v[156:159], v[164:167], v[48:51]
	v_mfma_f32_16x16x32_bf16 v[36:39], v[148:151], v[172:175], v[36:39]
	v_mfma_f32_16x16x32_bf16 v[32:35], v[156:159], v[172:175], v[32:35]
	v_mfma_f32_16x16x32_bf16 v[20:23], v[148:151], v[180:183], v[20:23]
	v_mfma_f32_16x16x32_bf16 v[16:19], v[156:159], v[180:183], v[16:19]
	v_mfma_f32_16x16x32_bf16 v[4:7], v[148:151], v[188:191], v[4:7]
	v_mfma_f32_16x16x32_bf16 v[0:3], v[156:159], v[188:191], v[0:3]
	s_setprio 0
	s_barrier
	s_add_i32 s76, s76, 2
	s_add_u32 s12, s12, 0x100
	s_addc_u32 s75, s75, 0
	s_cmp_gt_u32 s76, 41
	s_mov_b64 s[48:49], s[6:7]
	s_cbranch_scc0 .LBB0_461
	s_and_b64 vcc, exec, s[24:25]
	s_cbranch_vccz .LBB0_464
	s_barrier

; #define PG8_STAGE(bufoff, gbase, voff) do { _Pragma("unroll") for (int _i = 0; _i < 2; ++_i) \
;         __builtin_amdgcn_global_load_lds((const unsigned*)((const char*)(gbase) + (voff)[_i]), (PG8_LAS unsigned*)(lds + (bufoff) + ldsw + _i * 8192), 16, 0, 0); } while (0)
; #define PG8_LDA(dst, b, h) do { _Pragma("unroll") for (int m = 0; m < 4; ++m) _Pragma("unroll") for (int k = 0; k < 2; ++k) dst[m][k] = *(const PG8_LAS bf16x8*)(lds + PG8_SA(b, h) + aoff + m * 2048 + k * 1024); } while (0)
; #define PG8_LDB(dst, b, h) do { _Pragma("unroll") for (int n = 0; n < 2; ++n) _Pragma("unroll") for (int k = 0; k < 2; ++k) dst[n][k] = *(const PG8_LAS bf16x8*)(lds + PG8_SB(b, h) + boff + n * 2048 + k * 1024); } while (0)
; #define PG8_MMA(ai, bj, At, Bt) do { __builtin_amdgcn_s_setprio(1); _Pragma("unroll") for (int m = 0; m < 4; ++m) _Pragma("unroll") for (int n = 0; n < 2; ++n) _Pragma("unroll") for (int k = 0; k < 2; ++k) \
;         acc[ai][bj][m][n] = __builtin_amdgcn_mfma_f32_16x16x32_bf16(Bt[n][k], At[m][k], acc[ai][bj][m][n], 0, 0, 0); __builtin_amdgcn_s_setprio(0); } while (0)
; #define PG8_WAIT_V(n) asm volatile("s_waitcnt vmcnt(" #n ")" ::: "memory")
; #define PG8_WAIT_L(n) asm volatile("s_waitcnt lgkmcnt(" #n ")" ::: "memory")
; template <class Epi, class Sched, bool ALIGN_EPI = false, bool SP2 = false>
; __device__ __forceinline__ void gemm_phase(PG8_LAS unsigned char* lds, const Gemm g, const Sched& S, const Epi& E, int tid_in) {
;     ...
;             const bool last = (t == nt - 2);
;             const char* a1 = cA + (size_t)(t + 1) * kstep;
;             const char* a2 = last ? nA : cA + (size_t)(t + 2) * kstep; const char* b2 = last ? nB : cB + (size_t)(t + 2) * kstep;
;             const char* a3 = a2 + kstep; const char* b3 = b2 + kstep;
;             if (last && has_next) S.a_ready(nxt);
;             if constexpr (SP2) {
;             PG8_LDB(B0, 0, 0); PG8_LDB(B1, 0, 1); PG8_SCHED; PG8_LDA(At, 0, 0); PG8_STAGE(PG8_SA(1, 1), a1 + hstep, voffA);
;             PG8_WAIT_V(8); PG8_WAIT_L(0); PG8_BAR; PG8_MMA(0, 0, At, B0); PG8_MMA(0, 1, At, B1); PG8_BAR; PG8_SCHED;
;             PG8_LDA(At, 0, 1); PG8_STAGE(PG8_SB(0, 0), b2, voffB); PG8_STAGE(PG8_SB(0, 1), b2 + hstep, voffB); PG8_STAGE(PG8_SA(0, 0), a2, voffA);
;             PG8_WAIT_V(8); PG8_WAIT_L(0); PG8_BAR; PG8_MMA(1, 0, At, B0); PG8_MMA(1, 1, At, B1); PG8_BAR; PG8_SCHED;
.LBB0_564:
	s_add_u32 s48, s46, 0xfffc0080
	s_addc_u32 s49, s47, -1
	s_cmp_eq_u32 s52, 12
	s_cselect_b32 s51, s0, s49
	s_cselect_b32 s50, s1, s48
	s_cselect_b32 s49, s7, s45
	s_cselect_b32 s48, s31, s35
	s_add_i32 m0, s59, 0xc000
	ds_read_b128 v[128:131], v180
	global_load_lds_dwordx4 v158, s[46:47]
	s_add_i32 m0, s59, 0xe000
	ds_read_b128 v[132:135], v180 offset:1024
	global_load_lds_dwordx4 v160, s[46:47]
	ds_read_b128 v[136:139], v180 offset:2048
	ds_read_b128 v[140:143], v180 offset:3072
	ds_read_b128 v[166:169], v181
	ds_read_b128 v[170:173], v181 offset:1024
	ds_read_b128 v[174:177], v181 offset:2048
	ds_read_b128 v[184:187], v181 offset:3072
	ds_read_b128 v[188:191], v182
	ds_read_b128 v[192:195], v182 offset:1024
	ds_read_b128 v[196:199], v182 offset:2048
	ds_read_b128 v[200:203], v182 offset:3072
	ds_read_b128 v[204:207], v182 offset:4096
	ds_read_b128 v[208:211], v182 offset:5120
	ds_read_b128 v[212:215], v182 offset:6144
	ds_read_b128 v[216:219], v182 offset:7168
	s_waitcnt vmcnt(8)
	s_waitcnt lgkmcnt(0)
	s_barrier
	s_setprio 1
	v_mfma_f32_16x16x32_bf16 v[68:71], v[128:131], v[188:191], v[68:71]
	v_mfma_f32_16x16x32_bf16 v[56:59], v[136:139], v[188:191], v[56:59]
	v_mfma_f32_16x16x32_bf16 v[52:55], v[128:131], v[196:199], v[52:55]
	v_mfma_f32_16x16x32_bf16 v[48:51], v[136:139], v[196:199], v[48:51]
	v_mfma_f32_16x16x32_bf16 v[44:47], v[128:131], v[204:207], v[44:47]
	v_mfma_f32_16x16x32_bf16 v[40:43], v[136:139], v[204:207], v[40:43]
	v_mfma_f32_16x16x32_bf16 v[36:39], v[128:131], v[212:215], v[36:39]
	v_mfma_f32_16x16x32_bf16 v[32:35], v[136:139], v[212:215], v[32:35]
	v_mfma_f32_16x16x32_bf16 v[68:71], v[132:135], v[192:195], v[68:71]
	v_mfma_f32_16x16x32_bf16 v[56:59], v[140:143], v[192:195], v[56:59]
	v_mfma_f32_16x16x32_bf16 v[52:55], v[132:135], v[200:203], v[52:55]
	v_mfma_f32_16x16x32_bf16 v[48:51], v[140:143], v[200:203], v[48:51]
	v_mfma_f32_16x16x32_bf16 v[44:47], v[132:135], v[208:211], v[44:47]
	v_mfma_f32_16x16x32_bf16 v[40:43], v[140:143], v[208:211], v[40:43]
	v_mfma_f32_16x16x32_bf16 v[36:39], v[132:135], v[216:219], v[36:39]
	v_mfma_f32_16x16x32_bf16 v[32:35], v[140:143], v[216:219], v[32:35]
	s_setprio 0
	s_setprio 1
	v_mfma_f32_16x16x32_bf16 v[124:127], v[166:169], v[188:191], v[124:127]
	v_mfma_f32_16x16x32_bf16 v[120:123], v[174:177], v[188:191], v[120:123]
	v_mfma_f32_16x16x32_bf16 v[116:119], v[166:169], v[196:199], v[116:119]
	v_mfma_f32_16x16x32_bf16 v[112:115], v[174:177], v[196:199], v[112:115]
	v_mfma_f32_16x16x32_bf16 v[108:111], v[166:169], v[204:207], v[108:111]
	v_mfma_f32_16x16x32_bf16 v[104:107], v[174:177], v[204:207], v[104:107]
	v_mfma_f32_16x16x32_bf16 v[100:103], v[166:169], v[212:215], v[100:103]
	v_mfma_f32_16x16x32_bf16 v[96:99], v[174:177], v[212:215], v[96:99]
	v_mfma_f32_16x16x32_bf16 v[124:127], v[170:173], v[192:195], v[124:127]
	v_mfma_f32_16x16x32_bf16 v[120:123], v[184:187], v[192:195], v[120:123]
	v_mfma_f32_16x16x32_bf16 v[116:119], v[170:173], v[200:203], v[116:119]
	v_mfma_f32_16x16x32_bf16 v[112:115], v[184:187], v[200:203], v[112:115]
	v_mfma_f32_16x16x32_bf16 v[108:111], v[170:173], v[208:211], v[108:111]
	v_mfma_f32_16x16x32_bf16 v[104:107], v[184:187], v[208:211], v[104:107]
	v_mfma_f32_16x16x32_bf16 v[100:103], v[170:173], v[216:219], v[100:103]
	v_mfma_f32_16x16x32_bf16 v[96:99], v[184:187], v[216:219], v[96:99]
	s_setprio 0
	s_barrier
	s_add_u32 s98, s48, s14
	s_addc_u32 s99, s49, s15
	s_add_u32 s100, s50, s14
	s_addc_u32 s101, s51, s15
	s_mov_b32 m0, s59
	ds_read_b128 v[200:203], v182 offset:19456
	global_load_lds_dwordx4 v144, s[50:51]
	s_mov_b32 m0, s60
	ds_read_b128 v[204:207], v182 offset:20480
	global_load_lds_dwordx4 v148, s[50:51]
	s_add_i32 s53, s77, s29
	s_mov_b32 m0, s53
	ds_read_b128 v[188:191], v182 offset:16384
	global_load_lds_dwordx4 v146, s[48:49]
	s_add_i32 m0, s53, 0x2000
	s_add_u32 s88, s48, 0x40000
	s_addc_u32 s89, s49, 0
	s_add_i32 s53, s78, s29
	global_load_lds_dwordx4 v150, s[48:49]
	s_mov_b32 m0, s53
	ds_read_b128 v[192:195], v182 offset:17408
	global_load_lds_dwordx4 v146, s[88:89]
	s_add_i32 m0, s53, 0x2000
	ds_read_b128 v[196:199], v182 offset:18432
	global_load_lds_dwordx4 v150, s[88:89]
	ds_read_b128 v[208:211], v182 offset:21504
	ds_read_b128 v[212:215], v182 offset:22528
	ds_read_b128 v[216:219], v182 offset:23552
	s_waitcnt vmcnt(8)
	s_waitcnt lgkmcnt(0)
	s_barrier
	s_setprio 1
	v_mfma_f32_16x16x32_bf16 v[28:31], v[128:131], v[188:191], v[28:31]
	v_mfma_f32_16x16x32_bf16 v[24:27], v[136:139], v[188:191], v[24:27]
	v_mfma_f32_16x16x32_bf16 v[20:23], v[128:131], v[196:199], v[20:23]
	v_mfma_f32_16x16x32_bf16 v[16:19], v[136:139], v[196:199], v[16:19]
	v_mfma_f32_16x16x32_bf16 v[12:15], v[128:131], v[204:207], v[12:15]
	v_mfma_f32_16x16x32_bf16 v[8:11], v[136:139], v[204:207], v[8:11]
	v_mfma_f32_16x16x32_bf16 v[4:7], v[128:131], v[212:215], v[4:7]
	v_mfma_f32_16x16x32_bf16 v[0:3], v[136:139], v[212:215], v[0:3]
	v_mfma_f32_16x16x32_bf16 v[28:31], v[132:135], v[192:195], v[28:31]
	v_mfma_f32_16x16x32_bf16 v[24:27], v[140:143], v[192:195], v[24:27]
	v_mfma_f32_16x16x32_bf16 v[20:23], v[132:135], v[200:203], v[20:23]
	v_mfma_f32_16x16x32_bf16 v[16:19], v[140:143], v[200:203], v[16:19]
	v_mfma_f32_16x16x32_bf16 v[12:15], v[132:135], v[208:211], v[12:15]
	v_mfma_f32_16x16x32_bf16 v[8:11], v[140:143], v[208:211], v[8:11]
	v_mfma_f32_16x16x32_bf16 v[4:7], v[132:135], v[216:219], v[4:7]
	v_mfma_f32_16x16x32_bf16 v[0:3], v[140:143], v[216:219], v[0:3]
	s_setprio 0
	s_setprio 1
	v_mfma_f32_16x16x32_bf16 v[92:95], v[166:169], v[188:191], v[92:95]
	v_mfma_f32_16x16x32_bf16 v[88:91], v[174:177], v[188:191], v[88:91]
	v_mfma_f32_16x16x32_bf16 v[84:87], v[166:169], v[196:199], v[84:87]
	v_mfma_f32_16x16x32_bf16 v[80:83], v[174:177], v[196:199], v[80:83]
	v_mfma_f32_16x16x32_bf16 v[76:79], v[166:169], v[204:207], v[76:79]
	v_mfma_f32_16x16x32_bf16 v[72:75], v[174:177], v[204:207], v[72:75]
	v_mfma_f32_16x16x32_bf16 v[64:67], v[166:169], v[212:215], v[64:67]
	v_mfma_f32_16x16x32_bf16 v[60:63], v[174:177], v[212:215], v[60:63]
	v_mfma_f32_16x16x32_bf16 v[92:95], v[170:173], v[192:195], v[92:95]
	v_mfma_f32_16x16x32_bf16 v[88:91], v[184:187], v[192:195], v[88:91]
	v_mfma_f32_16x16x32_bf16 v[84:87], v[170:173], v[200:203], v[84:87]
	v_mfma_f32_16x16x32_bf16 v[80:83], v[184:187], v[200:203], v[80:83]
	v_mfma_f32_16x16x32_bf16 v[76:79], v[170:173], v[208:211], v[76:79]
	v_mfma_f32_16x16x32_bf16 v[72:75], v[184:187], v[208:211], v[72:75]
	v_mfma_f32_16x16x32_bf16 v[64:67], v[170:173], v[216:219], v[64:67]
	v_mfma_f32_16x16x32_bf16 v[60:63], v[184:187], v[216:219], v[60:63]
	s_setprio 0
	s_barrier
; #define PG8_STAGE(bufoff, gbase, voff) do { _Pragma("unroll") for (int _i = 0; _i < 2; ++_i) \
;         __builtin_amdgcn_global_load_lds((const unsigned*)((const char*)(gbase) + (voff)[_i]), (PG8_LAS unsigned*)(lds + (bufoff) + ldsw + _i * 8192), 16, 0, 0); } while (0)
; #define PG8_LDA(dst, b, h) do { _Pragma("unroll") for (int m = 0; m < 4; ++m) _Pragma("unroll") for (int k = 0; k < 2; ++k) dst[m][k] = *(const PG8_LAS bf16x8*)(lds + PG8_SA(b, h) + aoff + m * 2048 + k * 1024); } while (0)
; #define PG8_LDB(dst, b, h) do { _Pragma("unroll") for (int n = 0; n < 2; ++n) _Pragma("unroll") for (int k = 0; k < 2; ++k) dst[n][k] = *(const PG8_LAS bf16x8*)(lds + PG8_SB(b, h) + boff + n * 2048 + k * 1024); } while (0)
; #define PG8_MMA(ai, bj, At, Bt) do { __builtin_amdgcn_s_setprio(1); _Pragma("unroll") for (int m = 0; m < 4; ++m) _Pragma("unroll") for (int n = 0; n < 2; ++n) _Pragma("unroll") for (int k = 0; k < 2; ++k) \
;         acc[ai][bj][m][n] = __builtin_amdgcn_mfma_f32_16x16x32_bf16(Bt[n][k], At[m][k], acc[ai][bj][m][n], 0, 0, 0); __builtin_amdgcn_s_setprio(0); } while (0)
; #define PG8_WAIT_V(n) asm volatile("s_waitcnt vmcnt(" #n ")" ::: "memory")
; #define PG8_WAIT_L(n) asm volatile("s_waitcnt lgkmcnt(" #n ")" ::: "memory")
; #define PG8_BAR __builtin_amdgcn_s_barrier()
; #define PG8_SCHED __builtin_amdgcn_sched_barrier(0)
;     __device__ __forceinline__ void operator()(const f32x4 (&acc)[2][2][4][2], const Unit& u, int wr, int wc, int fr, int fq) const {
;         const int row0 = u.pm * BM + wr * 64 + fr; const int pn = u.pn;
;         if (pn == 19) {
;             if (wc != 0) return;
; template <class Epi, class Sched, bool ALIGN_EPI = false, bool SP2 = false>
; __device__ __forceinline__ void gemm_phase(PG8_LAS unsigned char* lds, const Gemm g, const Sched& S, const Epi& E, int tid_in) {
;     ...
;             PG8_LDB(B0, 1, 0); PG8_LDB(B1, 1, 1); PG8_SCHED; PG8_LDA(At, 1, 0); PG8_STAGE(PG8_SA(0, 1), a2 + hstep, voffA);
;             PG8_WAIT_V(8); PG8_WAIT_L(0); PG8_BAR; PG8_MMA(0, 0, At, B0); PG8_MMA(0, 1, At, B1); PG8_BAR; PG8_SCHED;
;             PG8_LDA(At, 1, 1); PG8_STAGE(PG8_SB(1, 0), b3, voffB); PG8_STAGE(PG8_SB(1, 1), b3 + hstep, voffB); PG8_STAGE(PG8_SA(1, 0), a3, voffA);
;             PG8_WAIT_V(8); PG8_WAIT_L(0); PG8_BAR; PG8_MMA(1, 0, At, B0); PG8_MMA(1, 1, At, B1); PG8_BAR; PG8_SCHED;
	s_add_i32 s53, 0, 0x18000
	s_add_i32 s88, 0, 0x1c000
	s_add_u32 s50, s50, 0x40000
	s_addc_u32 s51, s51, 0
	s_mov_b32 m0, s61
	s_nop 0
	global_load_lds_dwordx4 v144, s[50:51]
	s_mov_b32 m0, s62
	s_nop 0
	global_load_lds_dwordx4 v148, s[50:51]
	v_add_u32_e32 v140, s53, v179
	v_add_u32_e32 v184, s88, v179
	ds_read_b128 v[128:131], v140
	ds_read_b128 v[132:135], v140 offset:1024
	ds_read_b128 v[136:139], v140 offset:2048
	ds_read_b128 v[140:143], v140 offset:3072
	ds_read_b128 v[166:169], v184
	ds_read_b128 v[170:173], v184 offset:1024
	ds_read_b128 v[174:177], v184 offset:2048
	ds_read_b128 v[184:187], v184 offset:3072
	ds_read_b128 v[188:191], v182 offset:32768
	ds_read_b128 v[192:195], v182 offset:33792
	ds_read_b128 v[196:199], v182 offset:34816
	ds_read_b128 v[200:203], v182 offset:35840
	ds_read_b128 v[204:207], v182 offset:36864
	ds_read_b128 v[208:211], v182 offset:37888
	ds_read_b128 v[212:215], v182 offset:38912
	ds_read_b128 v[216:219], v182 offset:39936
	s_waitcnt vmcnt(8)
	s_waitcnt lgkmcnt(0)
	s_barrier
	s_setprio 1
	v_mfma_f32_16x16x32_bf16 v[68:71], v[128:131], v[188:191], v[68:71]
	v_mfma_f32_16x16x32_bf16 v[56:59], v[136:139], v[188:191], v[56:59]
	v_mfma_f32_16x16x32_bf16 v[52:55], v[128:131], v[196:199], v[52:55]
	v_mfma_f32_16x16x32_bf16 v[48:51], v[136:139], v[196:199], v[48:51]
	v_mfma_f32_16x16x32_bf16 v[44:47], v[128:131], v[204:207], v[44:47]
	v_mfma_f32_16x16x32_bf16 v[40:43], v[136:139], v[204:207], v[40:43]
	v_mfma_f32_16x16x32_bf16 v[36:39], v[128:131], v[212:215], v[36:39]
	v_mfma_f32_16x16x32_bf16 v[32:35], v[136:139], v[212:215], v[32:35]
	v_mfma_f32_16x16x32_bf16 v[68:71], v[132:135], v[192:195], v[68:71]
	v_mfma_f32_16x16x32_bf16 v[56:59], v[140:143], v[192:195], v[56:59]
	v_mfma_f32_16x16x32_bf16 v[52:55], v[132:135], v[200:203], v[52:55]
	v_mfma_f32_16x16x32_bf16 v[48:51], v[140:143], v[200:203], v[48:51]
	v_mfma_f32_16x16x32_bf16 v[44:47], v[132:135], v[208:211], v[44:47]
	v_mfma_f32_16x16x32_bf16 v[40:43], v[140:143], v[208:211], v[40:43]
	v_mfma_f32_16x16x32_bf16 v[36:39], v[132:135], v[216:219], v[36:39]
	v_mfma_f32_16x16x32_bf16 v[32:35], v[140:143], v[216:219], v[32:35]
	s_setprio 0
	s_setprio 1
	v_mfma_f32_16x16x32_bf16 v[124:127], v[166:169], v[188:191], v[124:127]
	v_mfma_f32_16x16x32_bf16 v[120:123], v[174:177], v[188:191], v[120:123]
	v_mfma_f32_16x16x32_bf16 v[116:119], v[166:169], v[196:199], v[116:119]
	v_mfma_f32_16x16x32_bf16 v[112:115], v[174:177], v[196:199], v[112:115]
	v_mfma_f32_16x16x32_bf16 v[108:111], v[166:169], v[204:207], v[108:111]
	v_mfma_f32_16x16x32_bf16 v[104:107], v[174:177], v[204:207], v[104:107]
	v_mfma_f32_16x16x32_bf16 v[100:103], v[166:169], v[212:215], v[100:103]
	v_mfma_f32_16x16x32_bf16 v[96:99], v[174:177], v[212:215], v[96:99]
	v_mfma_f32_16x16x32_bf16 v[124:127], v[170:173], v[192:195], v[124:127]
	v_mfma_f32_16x16x32_bf16 v[120:123], v[184:187], v[192:195], v[120:123]
	v_mfma_f32_16x16x32_bf16 v[116:119], v[170:173], v[200:203], v[116:119]
	v_mfma_f32_16x16x32_bf16 v[112:115], v[184:187], v[200:203], v[112:115]
	v_mfma_f32_16x16x32_bf16 v[108:111], v[170:173], v[208:211], v[108:111]
	v_mfma_f32_16x16x32_bf16 v[104:107], v[184:187], v[208:211], v[104:107]
	v_mfma_f32_16x16x32_bf16 v[100:103], v[170:173], v[216:219], v[100:103]
	v_mfma_f32_16x16x32_bf16 v[96:99], v[184:187], v[216:219], v[96:99]
	s_setprio 0
	s_barrier
	s_mov_b32 m0, s63
	ds_read_b128 v[200:203], v182 offset:52224
	global_load_lds_dwordx4 v144, s[100:101]
	s_mov_b32 m0, s64
	ds_read_b128 v[204:207], v182 offset:53248
	global_load_lds_dwordx4 v148, s[100:101]
	s_add_i32 s50, s53, s29
	s_mov_b32 m0, s50
	ds_read_b128 v[188:191], v182 offset:49152
	global_load_lds_dwordx4 v146, s[98:99]
	s_add_i32 m0, s50, 0x2000
	s_add_u32 s48, s48, 0x40080
	s_addc_u32 s49, s49, 0
	s_add_i32 s50, s88, s29
	global_load_lds_dwordx4 v150, s[98:99]
	s_mov_b32 m0, s50
	ds_read_b128 v[192:195], v182 offset:50176
	global_load_lds_dwordx4 v146, s[48:49]
	s_add_i32 m0, s50, 0x2000
	ds_read_b128 v[196:199], v182 offset:51200
	global_load_lds_dwordx4 v150, s[48:49]
	ds_read_b128 v[208:211], v182 offset:54272
	ds_read_b128 v[212:215], v182 offset:55296
	ds_read_b128 v[216:219], v182 offset:56320
	s_waitcnt vmcnt(8)
	s_waitcnt lgkmcnt(0)
	s_barrier
	s_setprio 1
	v_mfma_f32_16x16x32_bf16 v[28:31], v[128:131], v[188:191], v[28:31]
	v_mfma_f32_16x16x32_bf16 v[24:27], v[136:139], v[188:191], v[24:27]
	v_mfma_f32_16x16x32_bf16 v[20:23], v[128:131], v[196:199], v[20:23]
	v_mfma_f32_16x16x32_bf16 v[16:19], v[136:139], v[196:199], v[16:19]
	v_mfma_f32_16x16x32_bf16 v[12:15], v[128:131], v[204:207], v[12:15]
	v_mfma_f32_16x16x32_bf16 v[8:11], v[136:139], v[204:207], v[8:11]
	v_mfma_f32_16x16x32_bf16 v[4:7], v[128:131], v[212:215], v[4:7]
	v_mfma_f32_16x16x32_bf16 v[0:3], v[136:139], v[212:215], v[0:3]
	v_mfma_f32_16x16x32_bf16 v[28:31], v[132:135], v[192:195], v[28:31]
	v_mfma_f32_16x16x32_bf16 v[24:27], v[140:143], v[192:195], v[24:27]
	v_mfma_f32_16x16x32_bf16 v[20:23], v[132:135], v[200:203], v[20:23]
	v_mfma_f32_16x16x32_bf16 v[16:19], v[140:143], v[200:203], v[16:19]
	v_mfma_f32_16x16x32_bf16 v[12:15], v[132:135], v[208:211], v[12:15]
	v_mfma_f32_16x16x32_bf16 v[8:11], v[140:143], v[208:211], v[8:11]
	v_mfma_f32_16x16x32_bf16 v[4:7], v[132:135], v[216:219], v[4:7]
	v_mfma_f32_16x16x32_bf16 v[0:3], v[140:143], v[216:219], v[0:3]
	s_setprio 0
	s_setprio 1
	v_mfma_f32_16x16x32_bf16 v[92:95], v[166:169], v[188:191], v[92:95]
	v_mfma_f32_16x16x32_bf16 v[88:91], v[174:177], v[188:191], v[88:91]
	v_mfma_f32_16x16x32_bf16 v[84:87], v[166:169], v[196:199], v[84:87]
	v_mfma_f32_16x16x32_bf16 v[80:83], v[174:177], v[196:199], v[80:83]
	v_mfma_f32_16x16x32_bf16 v[76:79], v[166:169], v[204:207], v[76:79]
	v_mfma_f32_16x16x32_bf16 v[72:75], v[174:177], v[204:207], v[72:75]
	v_mfma_f32_16x16x32_bf16 v[64:67], v[166:169], v[212:215], v[64:67]
	v_mfma_f32_16x16x32_bf16 v[60:63], v[174:177], v[212:215], v[60:63]
	v_mfma_f32_16x16x32_bf16 v[92:95], v[170:173], v[192:195], v[92:95]
	v_mfma_f32_16x16x32_bf16 v[88:91], v[184:187], v[192:195], v[88:91]
	v_mfma_f32_16x16x32_bf16 v[84:87], v[170:173], v[200:203], v[84:87]
	v_mfma_f32_16x16x32_bf16 v[80:83], v[184:187], v[200:203], v[80:83]
	v_mfma_f32_16x16x32_bf16 v[76:79], v[170:173], v[208:211], v[76:79]
	v_mfma_f32_16x16x32_bf16 v[72:75], v[184:187], v[208:211], v[72:75]
	v_mfma_f32_16x16x32_bf16 v[64:67], v[170:173], v[216:219], v[64:67]
	v_mfma_f32_16x16x32_bf16 v[60:63], v[184:187], v[216:219], v[60:63]
	s_setprio 0
	s_barrier
	s_add_i32 s52, s52, 2
	s_add_u32 s46, s46, 0x100
	s_addc_u32 s47, s47, 0
	s_add_u32 s35, s35, 0x100
	s_addc_u32 s45, s45, 0
	s_cmp_gt_u32 s52, 13
	s_cbranch_scc0 .LBB0_564
	s_and_b64 vcc, exec, s[16:17]
	s_cbranch_vccnz .LBB0_568
	v_lshl_add_u32 v166, s44, 8, v178
	s_cmp_lg_u32 s6, 19
	s_mov_b64 s[44:45], -1
	s_cbranch_scc1 .LBB0_569

; #define PG8_STAGE(bufoff, gbase, voff) do { _Pragma("unroll") for (int _i = 0; _i < 2; ++_i) \
;         __builtin_amdgcn_global_load_lds((const unsigned*)((const char*)(gbase) + (voff)[_i]), (PG8_LAS unsigned*)(lds + (bufoff) + ldsw + _i * 8192), 16, 0, 0); } while (0)
; #define PG8_LDA(dst, b, h) do { _Pragma("unroll") for (int m = 0; m < 4; ++m) _Pragma("unroll") for (int k = 0; k < 2; ++k) dst[m][k] = *(const PG8_LAS bf16x8*)(lds + PG8_SA(b, h) + aoff + m * 2048 + k * 1024); } while (0)
; #define PG8_LDB(dst, b, h) do { _Pragma("unroll") for (int n = 0; n < 2; ++n) _Pragma("unroll") for (int k = 0; k < 2; ++k) dst[n][k] = *(const PG8_LAS bf16x8*)(lds + PG8_SB(b, h) + boff + n * 2048 + k * 1024); } while (0)
; #define PG8_MMA(ai, bj, At, Bt) do { __builtin_amdgcn_s_setprio(1); _Pragma("unroll") for (int m = 0; m < 4; ++m) _Pragma("unroll") for (int n = 0; n < 2; ++n) _Pragma("unroll") for (int k = 0; k < 2; ++k) \
;         acc[ai][bj][m][n] = __builtin_amdgcn_mfma_f32_16x16x32_bf16(Bt[n][k], At[m][k], acc[ai][bj][m][n], 0, 0, 0); __builtin_amdgcn_s_setprio(0); } while (0)
; #define PG8_WAIT_V(n) asm volatile("s_waitcnt vmcnt(" #n ")" ::: "memory")
; #define PG8_WAIT_L(n) asm volatile("s_waitcnt lgkmcnt(" #n ")" ::: "memory")
; template <class Epi, class Sched, bool ALIGN_EPI = false, bool SP2 = false>
; __device__ __forceinline__ void gemm_phase(PG8_LAS unsigned char* lds, const Gemm g, const Sched& S, const Epi& E, int tid_in) {
;     ...
;             const bool last = (t == nt - 2);
;             const char* a1 = cA + (size_t)(t + 1) * kstep;
;             const char* a2 = last ? nA : cA + (size_t)(t + 2) * kstep; const char* b2 = last ? nB : cB + (size_t)(t + 2) * kstep;
;             const char* a3 = a2 + kstep; const char* b3 = b2 + kstep;
;             if (last && has_next) S.a_ready(nxt);
;             if constexpr (SP2) {
;             PG8_LDB(B0, 0, 0); PG8_LDB(B1, 0, 1); PG8_SCHED; PG8_LDA(At, 0, 0); PG8_STAGE(PG8_SA(1, 1), a1 + hstep, voffA);
;             PG8_WAIT_V(8); PG8_WAIT_L(0); PG8_BAR; PG8_MMA(0, 0, At, B0); PG8_MMA(0, 1, At, B1); PG8_BAR; PG8_SCHED;
;             PG8_LDA(At, 0, 1); PG8_STAGE(PG8_SB(0, 0), b2, voffB); PG8_STAGE(PG8_SB(0, 1), b2 + hstep, voffB); PG8_STAGE(PG8_SA(0, 0), a2, voffA);
;             PG8_WAIT_V(8); PG8_WAIT_L(0); PG8_BAR; PG8_MMA(1, 0, At, B0); PG8_MMA(1, 1, At, B1); PG8_BAR; PG8_SCHED;
.LBB0_1148:
	s_add_u32 s34, s30, 0xfffc0080
	s_addc_u32 s35, s31, -1
	s_cmp_eq_u32 s60, 12
	s_cselect_b32 s37, s23, s35
	s_cselect_b32 s36, s29, s34
	s_cselect_b32 s35, s21, s59
	s_cselect_b32 s34, s57, s58
	s_add_i32 m0, s1, 0xc000
	ds_read_b128 v[128:131], v191
	global_load_lds_dwordx4 v160, s[30:31]
	s_add_i32 m0, s1, 0xe000
	ds_read_b128 v[132:135], v191 offset:1024
	global_load_lds_dwordx4 v162, s[30:31]
	ds_read_b128 v[136:139], v191 offset:2048
	ds_read_b128 v[140:143], v191 offset:3072
	ds_read_b128 v[144:147], v192
	ds_read_b128 v[148:151], v192 offset:1024
	ds_read_b128 v[168:171], v192 offset:2048
	ds_read_b128 v[172:175], v192 offset:3072
	ds_read_b128 v[176:179], v193
	ds_read_b128 v[180:183], v193 offset:1024
	ds_read_b128 v[194:197], v193 offset:2048
	ds_read_b128 v[198:201], v193 offset:3072
	ds_read_b128 v[202:205], v193 offset:4096
	ds_read_b128 v[206:209], v193 offset:5120
	ds_read_b128 v[210:213], v193 offset:6144
	ds_read_b128 v[214:217], v193 offset:7168
	s_waitcnt vmcnt(8)
	s_waitcnt lgkmcnt(0)
	s_barrier
	s_setprio 1
	v_mfma_f32_16x16x32_bf16 v[124:127], v[128:131], v[176:179], v[124:127]
	v_mfma_f32_16x16x32_bf16 v[120:123], v[136:139], v[176:179], v[120:123]
	v_mfma_f32_16x16x32_bf16 v[108:111], v[128:131], v[194:197], v[108:111]
	v_mfma_f32_16x16x32_bf16 v[104:107], v[136:139], v[194:197], v[104:107]
	v_mfma_f32_16x16x32_bf16 v[92:95], v[128:131], v[202:205], v[92:95]
	v_mfma_f32_16x16x32_bf16 v[88:91], v[136:139], v[202:205], v[88:91]
	v_mfma_f32_16x16x32_bf16 v[76:79], v[128:131], v[210:213], v[76:79]
	v_mfma_f32_16x16x32_bf16 v[72:75], v[136:139], v[210:213], v[72:75]
	v_mfma_f32_16x16x32_bf16 v[124:127], v[132:135], v[180:183], v[124:127]
	v_mfma_f32_16x16x32_bf16 v[120:123], v[140:143], v[180:183], v[120:123]
	v_mfma_f32_16x16x32_bf16 v[108:111], v[132:135], v[198:201], v[108:111]
	v_mfma_f32_16x16x32_bf16 v[104:107], v[140:143], v[198:201], v[104:107]
	v_mfma_f32_16x16x32_bf16 v[92:95], v[132:135], v[206:209], v[92:95]
	v_mfma_f32_16x16x32_bf16 v[88:91], v[140:143], v[206:209], v[88:91]
	v_mfma_f32_16x16x32_bf16 v[76:79], v[132:135], v[214:217], v[76:79]
	v_mfma_f32_16x16x32_bf16 v[72:75], v[140:143], v[214:217], v[72:75]
	s_setprio 0
	s_setprio 1
	v_mfma_f32_16x16x32_bf16 v[116:119], v[144:147], v[176:179], v[116:119]
	v_mfma_f32_16x16x32_bf16 v[112:115], v[168:171], v[176:179], v[112:115]
	v_mfma_f32_16x16x32_bf16 v[100:103], v[144:147], v[194:197], v[100:103]
	v_mfma_f32_16x16x32_bf16 v[96:99], v[168:171], v[194:197], v[96:99]
	v_mfma_f32_16x16x32_bf16 v[84:87], v[144:147], v[202:205], v[84:87]
	v_mfma_f32_16x16x32_bf16 v[80:83], v[168:171], v[202:205], v[80:83]
	v_mfma_f32_16x16x32_bf16 v[68:71], v[144:147], v[210:213], v[68:71]
	v_mfma_f32_16x16x32_bf16 v[64:67], v[168:171], v[210:213], v[64:67]
	v_mfma_f32_16x16x32_bf16 v[116:119], v[148:151], v[180:183], v[116:119]
	v_mfma_f32_16x16x32_bf16 v[112:115], v[172:175], v[180:183], v[112:115]
	v_mfma_f32_16x16x32_bf16 v[100:103], v[148:151], v[198:201], v[100:103]
	v_mfma_f32_16x16x32_bf16 v[96:99], v[172:175], v[198:201], v[96:99]
	v_mfma_f32_16x16x32_bf16 v[84:87], v[148:151], v[206:209], v[84:87]
	v_mfma_f32_16x16x32_bf16 v[80:83], v[172:175], v[206:209], v[80:83]
	v_mfma_f32_16x16x32_bf16 v[68:71], v[148:151], v[214:217], v[68:71]
	v_mfma_f32_16x16x32_bf16 v[64:67], v[172:175], v[214:217], v[64:67]
	s_setprio 0
	s_barrier
	s_add_u32 s98, s34, s16
	s_addc_u32 s99, s35, s17
	s_add_u32 s100, s36, s16
	s_addc_u32 s101, s37, s17
	s_mov_b32 m0, s1
	ds_read_b128 v[198:201], v193 offset:19456
	global_load_lds_dwordx4 v152, s[36:37]
	s_mov_b32 m0, s46
	ds_read_b128 v[202:205], v193 offset:20480
	global_load_lds_dwordx4 v156, s[36:37]
	s_add_i32 s61, s54, s0
	s_mov_b32 m0, s61
	ds_read_b128 v[176:179], v193 offset:16384
	global_load_lds_dwordx4 v154, s[34:35]
	s_add_i32 m0, s61, 0x2000
	s_add_u32 s62, s34, 0x40000
	s_addc_u32 s63, s35, 0
	s_add_i32 s61, s55, s0
	global_load_lds_dwordx4 v158, s[34:35]
	s_mov_b32 m0, s61
	ds_read_b128 v[180:183], v193 offset:17408
	global_load_lds_dwordx4 v154, s[62:63]
	s_add_i32 m0, s61, 0x2000
	ds_read_b128 v[194:197], v193 offset:18432
	global_load_lds_dwordx4 v158, s[62:63]
	ds_read_b128 v[206:209], v193 offset:21504
	ds_read_b128 v[210:213], v193 offset:22528
	ds_read_b128 v[214:217], v193 offset:23552
	s_waitcnt vmcnt(8)
	s_waitcnt lgkmcnt(0)
	s_barrier
	s_setprio 1
	v_mfma_f32_16x16x32_bf16 v[60:63], v[128:131], v[176:179], v[60:63]
	v_mfma_f32_16x16x32_bf16 v[56:59], v[136:139], v[176:179], v[56:59]
	v_mfma_f32_16x16x32_bf16 v[44:47], v[128:131], v[194:197], v[44:47]
	v_mfma_f32_16x16x32_bf16 v[40:43], v[136:139], v[194:197], v[40:43]
	v_mfma_f32_16x16x32_bf16 v[28:31], v[128:131], v[202:205], v[28:31]
	v_mfma_f32_16x16x32_bf16 v[24:27], v[136:139], v[202:205], v[24:27]
	v_mfma_f32_16x16x32_bf16 v[12:15], v[128:131], v[210:213], v[12:15]
	v_mfma_f32_16x16x32_bf16 v[8:11], v[136:139], v[210:213], v[8:11]
	v_mfma_f32_16x16x32_bf16 v[60:63], v[132:135], v[180:183], v[60:63]
	v_mfma_f32_16x16x32_bf16 v[56:59], v[140:143], v[180:183], v[56:59]
	v_mfma_f32_16x16x32_bf16 v[44:47], v[132:135], v[198:201], v[44:47]
	v_mfma_f32_16x16x32_bf16 v[40:43], v[140:143], v[198:201], v[40:43]
	v_mfma_f32_16x16x32_bf16 v[28:31], v[132:135], v[206:209], v[28:31]
	v_mfma_f32_16x16x32_bf16 v[24:27], v[140:143], v[206:209], v[24:27]
	v_mfma_f32_16x16x32_bf16 v[12:15], v[132:135], v[214:217], v[12:15]
	v_mfma_f32_16x16x32_bf16 v[8:11], v[140:143], v[214:217], v[8:11]
	s_setprio 0
	s_setprio 1
	v_mfma_f32_16x16x32_bf16 v[52:55], v[144:147], v[176:179], v[52:55]
	v_mfma_f32_16x16x32_bf16 v[48:51], v[168:171], v[176:179], v[48:51]
	v_mfma_f32_16x16x32_bf16 v[36:39], v[144:147], v[194:197], v[36:39]
	v_mfma_f32_16x16x32_bf16 v[32:35], v[168:171], v[194:197], v[32:35]
	v_mfma_f32_16x16x32_bf16 v[20:23], v[144:147], v[202:205], v[20:23]
	v_mfma_f32_16x16x32_bf16 v[16:19], v[168:171], v[202:205], v[16:19]
	v_mfma_f32_16x16x32_bf16 v[4:7], v[144:147], v[210:213], v[4:7]
	v_mfma_f32_16x16x32_bf16 v[0:3], v[168:171], v[210:213], v[0:3]
	v_mfma_f32_16x16x32_bf16 v[52:55], v[148:151], v[180:183], v[52:55]
	v_mfma_f32_16x16x32_bf16 v[48:51], v[172:175], v[180:183], v[48:51]
	v_mfma_f32_16x16x32_bf16 v[36:39], v[148:151], v[198:201], v[36:39]
	v_mfma_f32_16x16x32_bf16 v[32:35], v[172:175], v[198:201], v[32:35]
	v_mfma_f32_16x16x32_bf16 v[20:23], v[148:151], v[206:209], v[20:23]
	v_mfma_f32_16x16x32_bf16 v[16:19], v[172:175], v[206:209], v[16:19]
	v_mfma_f32_16x16x32_bf16 v[4:7], v[148:151], v[214:217], v[4:7]
	v_mfma_f32_16x16x32_bf16 v[0:3], v[172:175], v[214:217], v[0:3]
	s_setprio 0
	s_barrier
; #define PG8_STAGE(bufoff, gbase, voff) do { _Pragma("unroll") for (int _i = 0; _i < 2; ++_i) \
;         __builtin_amdgcn_global_load_lds((const unsigned*)((const char*)(gbase) + (voff)[_i]), (PG8_LAS unsigned*)(lds + (bufoff) + ldsw + _i * 8192), 16, 0, 0); } while (0)
; #define PG8_LDA(dst, b, h) do { _Pragma("unroll") for (int m = 0; m < 4; ++m) _Pragma("unroll") for (int k = 0; k < 2; ++k) dst[m][k] = *(const PG8_LAS bf16x8*)(lds + PG8_SA(b, h) + aoff + m * 2048 + k * 1024); } while (0)
; #define PG8_LDB(dst, b, h) do { _Pragma("unroll") for (int n = 0; n < 2; ++n) _Pragma("unroll") for (int k = 0; k < 2; ++k) dst[n][k] = *(const PG8_LAS bf16x8*)(lds + PG8_SB(b, h) + boff + n * 2048 + k * 1024); } while (0)
; #define PG8_MMA(ai, bj, At, Bt) do { __builtin_amdgcn_s_setprio(1); _Pragma("unroll") for (int m = 0; m < 4; ++m) _Pragma("unroll") for (int n = 0; n < 2; ++n) _Pragma("unroll") for (int k = 0; k < 2; ++k) \
;         acc[ai][bj][m][n] = __builtin_amdgcn_mfma_f32_16x16x32_bf16(Bt[n][k], At[m][k], acc[ai][bj][m][n], 0, 0, 0); __builtin_amdgcn_s_setprio(0); } while (0)
; #define PG8_WAIT_V(n) asm volatile("s_waitcnt vmcnt(" #n ")" ::: "memory")
; #define PG8_WAIT_L(n) asm volatile("s_waitcnt lgkmcnt(" #n ")" ::: "memory")
; #define PG8_BAR __builtin_amdgcn_s_barrier()
; #define PG8_SCHED __builtin_amdgcn_sched_barrier(0)
; template <class Epi, class Sched, bool ALIGN_EPI = false, bool SP2 = false>
; __device__ __forceinline__ void gemm_phase(PG8_LAS unsigned char* lds, const Gemm g, const Sched& S, const Epi& E, int tid_in) {
;     ...
;             PG8_LDB(B0, 1, 0); PG8_LDB(B1, 1, 1); PG8_SCHED; PG8_LDA(At, 1, 0); PG8_STAGE(PG8_SA(0, 1), a2 + hstep, voffA);
;             PG8_WAIT_V(8); PG8_WAIT_L(0); PG8_BAR; PG8_MMA(0, 0, At, B0); PG8_MMA(0, 1, At, B1); PG8_BAR; PG8_SCHED;
;             PG8_LDA(At, 1, 1); PG8_STAGE(PG8_SB(1, 0), b3, voffB); PG8_STAGE(PG8_SB(1, 1), b3 + hstep, voffB); PG8_STAGE(PG8_SA(1, 0), a3, voffA);
;             PG8_WAIT_V(8); PG8_WAIT_L(0); PG8_BAR; PG8_MMA(1, 0, At, B0); PG8_MMA(1, 1, At, B1); PG8_BAR; PG8_SCHED;
	s_add_i32 s61, 0, 0x18000
	s_add_i32 s62, 0, 0x1c000
	s_add_u32 s36, s36, 0x40000
	s_addc_u32 s37, s37, 0
	s_mov_b32 m0, s47
	s_nop 0
	global_load_lds_dwordx4 v152, s[36:37]
	s_mov_b32 m0, s48
	s_nop 0
	global_load_lds_dwordx4 v156, s[36:37]
	v_add_u32_e32 v140, s61, v187
	v_add_u32_e32 v172, s62, v187
	ds_read_b128 v[128:131], v140
	ds_read_b128 v[132:135], v140 offset:1024
	ds_read_b128 v[136:139], v140 offset:2048
	ds_read_b128 v[140:143], v140 offset:3072
	ds_read_b128 v[144:147], v172
	ds_read_b128 v[148:151], v172 offset:1024
	ds_read_b128 v[168:171], v172 offset:2048
	ds_read_b128 v[172:175], v172 offset:3072
	ds_read_b128 v[176:179], v193 offset:32768
	ds_read_b128 v[180:183], v193 offset:33792
	ds_read_b128 v[194:197], v193 offset:34816
	ds_read_b128 v[198:201], v193 offset:35840
	ds_read_b128 v[202:205], v193 offset:36864
	ds_read_b128 v[206:209], v193 offset:37888
	ds_read_b128 v[210:213], v193 offset:38912
	ds_read_b128 v[214:217], v193 offset:39936
	s_waitcnt vmcnt(8)
	s_waitcnt lgkmcnt(0)
	s_barrier
	s_setprio 1
	v_mfma_f32_16x16x32_bf16 v[124:127], v[128:131], v[176:179], v[124:127]
	v_mfma_f32_16x16x32_bf16 v[120:123], v[136:139], v[176:179], v[120:123]
	v_mfma_f32_16x16x32_bf16 v[108:111], v[128:131], v[194:197], v[108:111]
	v_mfma_f32_16x16x32_bf16 v[104:107], v[136:139], v[194:197], v[104:107]
	v_mfma_f32_16x16x32_bf16 v[92:95], v[128:131], v[202:205], v[92:95]
	v_mfma_f32_16x16x32_bf16 v[88:91], v[136:139], v[202:205], v[88:91]
	v_mfma_f32_16x16x32_bf16 v[76:79], v[128:131], v[210:213], v[76:79]
	v_mfma_f32_16x16x32_bf16 v[72:75], v[136:139], v[210:213], v[72:75]
	v_mfma_f32_16x16x32_bf16 v[124:127], v[132:135], v[180:183], v[124:127]
	v_mfma_f32_16x16x32_bf16 v[120:123], v[140:143], v[180:183], v[120:123]
	v_mfma_f32_16x16x32_bf16 v[108:111], v[132:135], v[198:201], v[108:111]
	v_mfma_f32_16x16x32_bf16 v[104:107], v[140:143], v[198:201], v[104:107]
	v_mfma_f32_16x16x32_bf16 v[92:95], v[132:135], v[206:209], v[92:95]
	v_mfma_f32_16x16x32_bf16 v[88:91], v[140:143], v[206:209], v[88:91]
	v_mfma_f32_16x16x32_bf16 v[76:79], v[132:135], v[214:217], v[76:79]
	v_mfma_f32_16x16x32_bf16 v[72:75], v[140:143], v[214:217], v[72:75]
	s_setprio 0
	s_setprio 1
	v_mfma_f32_16x16x32_bf16 v[116:119], v[144:147], v[176:179], v[116:119]
	v_mfma_f32_16x16x32_bf16 v[112:115], v[168:171], v[176:179], v[112:115]
	v_mfma_f32_16x16x32_bf16 v[100:103], v[144:147], v[194:197], v[100:103]
	v_mfma_f32_16x16x32_bf16 v[96:99], v[168:171], v[194:197], v[96:99]
	v_mfma_f32_16x16x32_bf16 v[84:87], v[144:147], v[202:205], v[84:87]
	v_mfma_f32_16x16x32_bf16 v[80:83], v[168:171], v[202:205], v[80:83]
	v_mfma_f32_16x16x32_bf16 v[68:71], v[144:147], v[210:213], v[68:71]
	v_mfma_f32_16x16x32_bf16 v[64:67], v[168:171], v[210:213], v[64:67]
	v_mfma_f32_16x16x32_bf16 v[116:119], v[148:151], v[180:183], v[116:119]
	v_mfma_f32_16x16x32_bf16 v[112:115], v[172:175], v[180:183], v[112:115]
	v_mfma_f32_16x16x32_bf16 v[100:103], v[148:151], v[198:201], v[100:103]
	v_mfma_f32_16x16x32_bf16 v[96:99], v[172:175], v[198:201], v[96:99]
	v_mfma_f32_16x16x32_bf16 v[84:87], v[148:151], v[206:209], v[84:87]
	v_mfma_f32_16x16x32_bf16 v[80:83], v[172:175], v[206:209], v[80:83]
	v_mfma_f32_16x16x32_bf16 v[68:71], v[148:151], v[214:217], v[68:71]
	v_mfma_f32_16x16x32_bf16 v[64:67], v[172:175], v[214:217], v[64:67]
	s_setprio 0
	s_barrier
	s_mov_b32 m0, s50
	ds_read_b128 v[198:201], v193 offset:52224
	global_load_lds_dwordx4 v152, s[100:101]
	s_mov_b32 m0, s51
	ds_read_b128 v[202:205], v193 offset:53248
	global_load_lds_dwordx4 v156, s[100:101]
	s_add_i32 s36, s61, s0
	s_mov_b32 m0, s36
	ds_read_b128 v[176:179], v193 offset:49152
	global_load_lds_dwordx4 v154, s[98:99]
	s_add_i32 m0, s36, 0x2000
	s_add_u32 s34, s34, 0x40080
	s_addc_u32 s35, s35, 0
	s_add_i32 s36, s62, s0
	global_load_lds_dwordx4 v158, s[98:99]
	s_mov_b32 m0, s36
	ds_read_b128 v[180:183], v193 offset:50176
	global_load_lds_dwordx4 v154, s[34:35]
	s_add_i32 m0, s36, 0x2000
	ds_read_b128 v[194:197], v193 offset:51200
	global_load_lds_dwordx4 v158, s[34:35]
	ds_read_b128 v[206:209], v193 offset:54272
	ds_read_b128 v[210:213], v193 offset:55296
	ds_read_b128 v[214:217], v193 offset:56320
	s_waitcnt vmcnt(8)
	s_waitcnt lgkmcnt(0)
	s_barrier
	s_setprio 1
	v_mfma_f32_16x16x32_bf16 v[60:63], v[128:131], v[176:179], v[60:63]
	v_mfma_f32_16x16x32_bf16 v[56:59], v[136:139], v[176:179], v[56:59]
	v_mfma_f32_16x16x32_bf16 v[44:47], v[128:131], v[194:197], v[44:47]
	v_mfma_f32_16x16x32_bf16 v[40:43], v[136:139], v[194:197], v[40:43]
	v_mfma_f32_16x16x32_bf16 v[28:31], v[128:131], v[202:205], v[28:31]
	v_mfma_f32_16x16x32_bf16 v[24:27], v[136:139], v[202:205], v[24:27]
	v_mfma_f32_16x16x32_bf16 v[12:15], v[128:131], v[210:213], v[12:15]
	v_mfma_f32_16x16x32_bf16 v[8:11], v[136:139], v[210:213], v[8:11]
	v_mfma_f32_16x16x32_bf16 v[60:63], v[132:135], v[180:183], v[60:63]
	v_mfma_f32_16x16x32_bf16 v[56:59], v[140:143], v[180:183], v[56:59]
	v_mfma_f32_16x16x32_bf16 v[44:47], v[132:135], v[198:201], v[44:47]
	v_mfma_f32_16x16x32_bf16 v[40:43], v[140:143], v[198:201], v[40:43]
	v_mfma_f32_16x16x32_bf16 v[28:31], v[132:135], v[206:209], v[28:31]
	v_mfma_f32_16x16x32_bf16 v[24:27], v[140:143], v[206:209], v[24:27]
	v_mfma_f32_16x16x32_bf16 v[12:15], v[132:135], v[214:217], v[12:15]
	v_mfma_f32_16x16x32_bf16 v[8:11], v[140:143], v[214:217], v[8:11]
	s_setprio 0
	s_setprio 1
	v_mfma_f32_16x16x32_bf16 v[52:55], v[144:147], v[176:179], v[52:55]
	v_mfma_f32_16x16x32_bf16 v[48:51], v[168:171], v[176:179], v[48:51]
	v_mfma_f32_16x16x32_bf16 v[36:39], v[144:147], v[194:197], v[36:39]
	v_mfma_f32_16x16x32_bf16 v[32:35], v[168:171], v[194:197], v[32:35]
	v_mfma_f32_16x16x32_bf16 v[20:23], v[144:147], v[202:205], v[20:23]
	v_mfma_f32_16x16x32_bf16 v[16:19], v[168:171], v[202:205], v[16:19]
	v_mfma_f32_16x16x32_bf16 v[4:7], v[144:147], v[210:213], v[4:7]
	v_mfma_f32_16x16x32_bf16 v[0:3], v[168:171], v[210:213], v[0:3]
	v_mfma_f32_16x16x32_bf16 v[52:55], v[148:151], v[180:183], v[52:55]
	v_mfma_f32_16x16x32_bf16 v[48:51], v[172:175], v[180:183], v[48:51]
	v_mfma_f32_16x16x32_bf16 v[36:39], v[148:151], v[198:201], v[36:39]
	v_mfma_f32_16x16x32_bf16 v[32:35], v[172:175], v[198:201], v[32:35]
	v_mfma_f32_16x16x32_bf16 v[20:23], v[148:151], v[206:209], v[20:23]
	v_mfma_f32_16x16x32_bf16 v[16:19], v[172:175], v[206:209], v[16:19]
	v_mfma_f32_16x16x32_bf16 v[4:7], v[148:151], v[214:217], v[4:7]
	v_mfma_f32_16x16x32_bf16 v[0:3], v[172:175], v[214:217], v[0:3]
	s_setprio 0
	s_barrier
	s_add_i32 s60, s60, 2
	s_add_u32 s30, s30, 0x100
	s_addc_u32 s31, s31, 0
	s_add_u32 s58, s58, 0x100
	s_addc_u32 s59, s59, 0
	s_cmp_gt_u32 s60, 13
	s_cbranch_scc0 .LBB0_1148
	s_and_b64 vcc, exec, s[18:19]
	s_cbranch_vccz .LBB0_1151
	s_barrier

; #define PG8_STAGE(bufoff, gbase, voff) do { _Pragma("unroll") for (int _i = 0; _i < 2; ++_i) \
;         __builtin_amdgcn_global_load_lds((const unsigned*)((const char*)(gbase) + (voff)[_i]), (PG8_LAS unsigned*)(lds + (bufoff) + ldsw + _i * 8192), 16, 0, 0); } while (0)
; #define PG8_LDA(dst, b, h) do { _Pragma("unroll") for (int m = 0; m < 4; ++m) _Pragma("unroll") for (int k = 0; k < 2; ++k) dst[m][k] = *(const PG8_LAS bf16x8*)(lds + PG8_SA(b, h) + aoff + m * 2048 + k * 1024); } while (0)
; #define PG8_LDB(dst, b, h) do { _Pragma("unroll") for (int n = 0; n < 2; ++n) _Pragma("unroll") for (int k = 0; k < 2; ++k) dst[n][k] = *(const PG8_LAS bf16x8*)(lds + PG8_SB(b, h) + boff + n * 2048 + k * 1024); } while (0)
; #define PG8_MMA(ai, bj, At, Bt) do { __builtin_amdgcn_s_setprio(1); _Pragma("unroll") for (int m = 0; m < 4; ++m) _Pragma("unroll") for (int n = 0; n < 2; ++n) _Pragma("unroll") for (int k = 0; k < 2; ++k) \
;         acc[ai][bj][m][n] = __builtin_amdgcn_mfma_f32_16x16x32_bf16(Bt[n][k], At[m][k], acc[ai][bj][m][n], 0, 0, 0); __builtin_amdgcn_s_setprio(0); } while (0)
; #define PG8_WAIT_V(n) asm volatile("s_waitcnt vmcnt(" #n ")" ::: "memory")
; #define PG8_WAIT_L(n) asm volatile("s_waitcnt lgkmcnt(" #n ")" ::: "memory")
; template <class Epi, class Sched, bool ALIGN_EPI = false, bool SP2 = false>
; __device__ __forceinline__ void gemm_phase(PG8_LAS unsigned char* lds, const Gemm g, const Sched& S, const Epi& E, int tid_in) {
;     ...
;             const bool last = (t == nt - 2);
;             const char* a1 = cA + (size_t)(t + 1) * kstep;
;             const char* a2 = last ? nA : cA + (size_t)(t + 2) * kstep; const char* b2 = last ? nB : cB + (size_t)(t + 2) * kstep;
;             const char* a3 = a2 + kstep; const char* b3 = b2 + kstep;
;             if (last && has_next) S.a_ready(nxt);
;             if constexpr (SP2) {
;             PG8_LDB(B0, 0, 0); PG8_LDB(B1, 0, 1); PG8_SCHED; PG8_LDA(At, 0, 0); PG8_STAGE(PG8_SA(1, 1), a1 + hstep, voffA);
;             PG8_WAIT_V(8); PG8_WAIT_L(0); PG8_BAR; PG8_MMA(0, 0, At, B0); PG8_MMA(0, 1, At, B1); PG8_BAR; PG8_SCHED;
;             PG8_LDA(At, 0, 1); PG8_STAGE(PG8_SB(0, 0), b2, voffB); PG8_STAGE(PG8_SB(0, 1), b2 + hstep, voffB); PG8_STAGE(PG8_SA(0, 0), a2, voffA);
;             PG8_WAIT_V(8); PG8_WAIT_L(0); PG8_BAR; PG8_MMA(1, 0, At, B0); PG8_MMA(1, 1, At, B1); PG8_BAR; PG8_SCHED;
.LBB0_1238:
	s_add_u32 s26, s24, 0xfffc0080
	s_addc_u32 s27, s25, -1
	s_cmp_eq_u32 s58, 12
	s_cselect_b32 s29, s17, s27
	s_cselect_b32 s28, s54, s26
	s_cselect_b32 s27, s15, s57
	s_cselect_b32 s26, s55, s56
	s_add_i32 m0, s23, 0xc000
	ds_read_b128 v[144:147], v154
	global_load_lds_dwordx4 v136, s[24:25]
	s_add_i32 m0, s23, 0xe000
	ds_read_b128 v[158:161], v154 offset:1024
	global_load_lds_dwordx4 v138, s[24:25]
	ds_read_b128 v[162:165], v154 offset:2048
	ds_read_b128 v[166:169], v154 offset:3072
	ds_read_b128 v[170:173], v155
	ds_read_b128 v[174:177], v155 offset:1024
	ds_read_b128 v[178:181], v155 offset:2048
	ds_read_b128 v[182:185], v155 offset:3072
	ds_read_b128 v[186:189], v156
	ds_read_b128 v[190:193], v156 offset:1024
	ds_read_b128 v[194:197], v156 offset:2048
	ds_read_b128 v[198:201], v156 offset:3072
	ds_read_b128 v[202:205], v156 offset:4096
	ds_read_b128 v[206:209], v156 offset:5120
	ds_read_b128 v[210:213], v156 offset:6144
	ds_read_b128 v[214:217], v156 offset:7168
	s_waitcnt vmcnt(8)
	s_waitcnt lgkmcnt(0)
	s_barrier
	s_setprio 1
	v_mfma_f32_16x16x32_bf16 v[124:127], v[144:147], v[186:189], v[124:127]
	v_mfma_f32_16x16x32_bf16 v[120:123], v[162:165], v[186:189], v[120:123]
	v_mfma_f32_16x16x32_bf16 v[108:111], v[144:147], v[194:197], v[108:111]
	v_mfma_f32_16x16x32_bf16 v[104:107], v[162:165], v[194:197], v[104:107]
	v_mfma_f32_16x16x32_bf16 v[92:95], v[144:147], v[202:205], v[92:95]
	v_mfma_f32_16x16x32_bf16 v[88:91], v[162:165], v[202:205], v[88:91]
	v_mfma_f32_16x16x32_bf16 v[76:79], v[144:147], v[210:213], v[76:79]
	v_mfma_f32_16x16x32_bf16 v[72:75], v[162:165], v[210:213], v[72:75]
	v_mfma_f32_16x16x32_bf16 v[124:127], v[158:161], v[190:193], v[124:127]
	v_mfma_f32_16x16x32_bf16 v[120:123], v[166:169], v[190:193], v[120:123]
	v_mfma_f32_16x16x32_bf16 v[108:111], v[158:161], v[198:201], v[108:111]
	v_mfma_f32_16x16x32_bf16 v[104:107], v[166:169], v[198:201], v[104:107]
	v_mfma_f32_16x16x32_bf16 v[92:95], v[158:161], v[206:209], v[92:95]
	v_mfma_f32_16x16x32_bf16 v[88:91], v[166:169], v[206:209], v[88:91]
	v_mfma_f32_16x16x32_bf16 v[76:79], v[158:161], v[214:217], v[76:79]
	v_mfma_f32_16x16x32_bf16 v[72:75], v[166:169], v[214:217], v[72:75]
	s_setprio 0
	s_setprio 1
	v_mfma_f32_16x16x32_bf16 v[116:119], v[170:173], v[186:189], v[116:119]
	v_mfma_f32_16x16x32_bf16 v[112:115], v[178:181], v[186:189], v[112:115]
	v_mfma_f32_16x16x32_bf16 v[100:103], v[170:173], v[194:197], v[100:103]
	v_mfma_f32_16x16x32_bf16 v[96:99], v[178:181], v[194:197], v[96:99]
	v_mfma_f32_16x16x32_bf16 v[84:87], v[170:173], v[202:205], v[84:87]
	v_mfma_f32_16x16x32_bf16 v[80:83], v[178:181], v[202:205], v[80:83]
	v_mfma_f32_16x16x32_bf16 v[68:71], v[170:173], v[210:213], v[68:71]
	v_mfma_f32_16x16x32_bf16 v[64:67], v[178:181], v[210:213], v[64:67]
	v_mfma_f32_16x16x32_bf16 v[116:119], v[174:177], v[190:193], v[116:119]
	v_mfma_f32_16x16x32_bf16 v[112:115], v[182:185], v[190:193], v[112:115]
	v_mfma_f32_16x16x32_bf16 v[100:103], v[174:177], v[198:201], v[100:103]
	v_mfma_f32_16x16x32_bf16 v[96:99], v[182:185], v[198:201], v[96:99]
	v_mfma_f32_16x16x32_bf16 v[84:87], v[174:177], v[206:209], v[84:87]
	v_mfma_f32_16x16x32_bf16 v[80:83], v[182:185], v[206:209], v[80:83]
	v_mfma_f32_16x16x32_bf16 v[68:71], v[174:177], v[214:217], v[68:71]
	v_mfma_f32_16x16x32_bf16 v[64:67], v[182:185], v[214:217], v[64:67]
	s_setprio 0
	s_barrier
	s_add_u32 s98, s26, s10
	s_addc_u32 s99, s27, s11
	s_add_u32 s100, s28, s10
	s_addc_u32 s101, s29, s11
	s_mov_b32 m0, s23
	ds_read_b128 v[198:201], v156 offset:19456
	global_load_lds_dwordx4 v134, s[28:29]
	s_mov_b32 m0, s37
	ds_read_b128 v[202:205], v156 offset:20480
	global_load_lds_dwordx4 v130, s[28:29]
	s_add_i32 s59, s47, s0
	s_mov_b32 m0, s59
	ds_read_b128 v[186:189], v156 offset:16384
	global_load_lds_dwordx4 v132, s[26:27]
	s_add_i32 m0, s59, 0x2000
	s_add_u32 s60, s26, 0x40000
	s_addc_u32 s61, s27, 0
	s_add_i32 s59, s48, s0
	global_load_lds_dwordx4 v128, s[26:27]
	s_mov_b32 m0, s59
	ds_read_b128 v[190:193], v156 offset:17408
	global_load_lds_dwordx4 v132, s[60:61]
	s_add_i32 m0, s59, 0x2000
	ds_read_b128 v[194:197], v156 offset:18432
	global_load_lds_dwordx4 v128, s[60:61]
	ds_read_b128 v[206:209], v156 offset:21504
	ds_read_b128 v[210:213], v156 offset:22528
	ds_read_b128 v[214:217], v156 offset:23552
	s_waitcnt vmcnt(8)
	s_waitcnt lgkmcnt(0)
	s_barrier
	s_setprio 1
	v_mfma_f32_16x16x32_bf16 v[60:63], v[144:147], v[186:189], v[60:63]
	v_mfma_f32_16x16x32_bf16 v[56:59], v[162:165], v[186:189], v[56:59]
	v_mfma_f32_16x16x32_bf16 v[44:47], v[144:147], v[194:197], v[44:47]
	v_mfma_f32_16x16x32_bf16 v[40:43], v[162:165], v[194:197], v[40:43]
	v_mfma_f32_16x16x32_bf16 v[28:31], v[144:147], v[202:205], v[28:31]
	v_mfma_f32_16x16x32_bf16 v[24:27], v[162:165], v[202:205], v[24:27]
	v_mfma_f32_16x16x32_bf16 v[12:15], v[144:147], v[210:213], v[12:15]
	v_mfma_f32_16x16x32_bf16 v[8:11], v[162:165], v[210:213], v[8:11]
	v_mfma_f32_16x16x32_bf16 v[60:63], v[158:161], v[190:193], v[60:63]
	v_mfma_f32_16x16x32_bf16 v[56:59], v[166:169], v[190:193], v[56:59]
	v_mfma_f32_16x16x32_bf16 v[44:47], v[158:161], v[198:201], v[44:47]
	v_mfma_f32_16x16x32_bf16 v[40:43], v[166:169], v[198:201], v[40:43]
	v_mfma_f32_16x16x32_bf16 v[28:31], v[158:161], v[206:209], v[28:31]
	v_mfma_f32_16x16x32_bf16 v[24:27], v[166:169], v[206:209], v[24:27]
	v_mfma_f32_16x16x32_bf16 v[12:15], v[158:161], v[214:217], v[12:15]
	v_mfma_f32_16x16x32_bf16 v[8:11], v[166:169], v[214:217], v[8:11]
	s_setprio 0
	s_setprio 1
	v_mfma_f32_16x16x32_bf16 v[52:55], v[170:173], v[186:189], v[52:55]
	v_mfma_f32_16x16x32_bf16 v[48:51], v[178:181], v[186:189], v[48:51]
	v_mfma_f32_16x16x32_bf16 v[36:39], v[170:173], v[194:197], v[36:39]
	v_mfma_f32_16x16x32_bf16 v[32:35], v[178:181], v[194:197], v[32:35]
	v_mfma_f32_16x16x32_bf16 v[20:23], v[170:173], v[202:205], v[20:23]
	v_mfma_f32_16x16x32_bf16 v[16:19], v[178:181], v[202:205], v[16:19]
	v_mfma_f32_16x16x32_bf16 v[4:7], v[170:173], v[210:213], v[4:7]
	v_mfma_f32_16x16x32_bf16 v[0:3], v[178:181], v[210:213], v[0:3]
	v_mfma_f32_16x16x32_bf16 v[52:55], v[174:177], v[190:193], v[52:55]
	v_mfma_f32_16x16x32_bf16 v[48:51], v[182:185], v[190:193], v[48:51]
	v_mfma_f32_16x16x32_bf16 v[36:39], v[174:177], v[198:201], v[36:39]
	v_mfma_f32_16x16x32_bf16 v[32:35], v[182:185], v[198:201], v[32:35]
	v_mfma_f32_16x16x32_bf16 v[20:23], v[174:177], v[206:209], v[20:23]
	v_mfma_f32_16x16x32_bf16 v[16:19], v[182:185], v[206:209], v[16:19]
	v_mfma_f32_16x16x32_bf16 v[4:7], v[174:177], v[214:217], v[4:7]
	v_mfma_f32_16x16x32_bf16 v[0:3], v[182:185], v[214:217], v[0:3]
	s_setprio 0
	s_barrier
; #define PG8_STAGE(bufoff, gbase, voff) do { _Pragma("unroll") for (int _i = 0; _i < 2; ++_i) \
;         __builtin_amdgcn_global_load_lds((const unsigned*)((const char*)(gbase) + (voff)[_i]), (PG8_LAS unsigned*)(lds + (bufoff) + ldsw + _i * 8192), 16, 0, 0); } while (0)
; #define PG8_LDA(dst, b, h) do { _Pragma("unroll") for (int m = 0; m < 4; ++m) _Pragma("unroll") for (int k = 0; k < 2; ++k) dst[m][k] = *(const PG8_LAS bf16x8*)(lds + PG8_SA(b, h) + aoff + m * 2048 + k * 1024); } while (0)
; #define PG8_LDB(dst, b, h) do { _Pragma("unroll") for (int n = 0; n < 2; ++n) _Pragma("unroll") for (int k = 0; k < 2; ++k) dst[n][k] = *(const PG8_LAS bf16x8*)(lds + PG8_SB(b, h) + boff + n * 2048 + k * 1024); } while (0)
; #define PG8_MMA(ai, bj, At, Bt) do { __builtin_amdgcn_s_setprio(1); _Pragma("unroll") for (int m = 0; m < 4; ++m) _Pragma("unroll") for (int n = 0; n < 2; ++n) _Pragma("unroll") for (int k = 0; k < 2; ++k) \
;         acc[ai][bj][m][n] = __builtin_amdgcn_mfma_f32_16x16x32_bf16(Bt[n][k], At[m][k], acc[ai][bj][m][n], 0, 0, 0); __builtin_amdgcn_s_setprio(0); } while (0)
; #define PG8_WAIT_V(n) asm volatile("s_waitcnt vmcnt(" #n ")" ::: "memory")
; #define PG8_WAIT_L(n) asm volatile("s_waitcnt lgkmcnt(" #n ")" ::: "memory")
; #define PG8_BAR __builtin_amdgcn_s_barrier()
; #define PG8_SCHED __builtin_amdgcn_sched_barrier(0)
; template <class Epi, class Sched, bool ALIGN_EPI = false, bool SP2 = false>
; __device__ __forceinline__ void gemm_phase(PG8_LAS unsigned char* lds, const Gemm g, const Sched& S, const Epi& E, int tid_in) {
;     ...
;             PG8_LDB(B0, 1, 0); PG8_LDB(B1, 1, 1); PG8_SCHED; PG8_LDA(At, 1, 0); PG8_STAGE(PG8_SA(0, 1), a2 + hstep, voffA);
;             PG8_WAIT_V(8); PG8_WAIT_L(0); PG8_BAR; PG8_MMA(0, 0, At, B0); PG8_MMA(0, 1, At, B1); PG8_BAR; PG8_SCHED;
;             PG8_LDA(At, 1, 1); PG8_STAGE(PG8_SB(1, 0), b3, voffB); PG8_STAGE(PG8_SB(1, 1), b3 + hstep, voffB); PG8_STAGE(PG8_SA(1, 0), a3, voffA);
;             PG8_WAIT_V(8); PG8_WAIT_L(0); PG8_BAR; PG8_MMA(1, 0, At, B0); PG8_MMA(1, 1, At, B1); PG8_BAR; PG8_SCHED;
	s_add_i32 s59, 0, 0x18000
	s_add_i32 s60, 0, 0x1c000
	s_add_u32 s28, s28, 0x40000
	s_addc_u32 s29, s29, 0
	s_mov_b32 m0, s38
	v_add_u32_e32 v157, s59, v151
	global_load_lds_dwordx4 v134, s[28:29]
	s_mov_b32 m0, s39
	ds_read_b128 v[144:147], v157
	global_load_lds_dwordx4 v130, s[28:29]
	ds_read_b128 v[158:161], v157 offset:1024
	ds_read_b128 v[162:165], v157 offset:2048
	ds_read_b128 v[166:169], v157 offset:3072
	v_add_u32_e32 v157, s60, v151
	ds_read_b128 v[170:173], v157
	ds_read_b128 v[174:177], v157 offset:1024
	ds_read_b128 v[178:181], v157 offset:2048
	ds_read_b128 v[182:185], v157 offset:3072
	ds_read_b128 v[186:189], v156 offset:32768
	ds_read_b128 v[190:193], v156 offset:33792
	ds_read_b128 v[194:197], v156 offset:34816
	ds_read_b128 v[198:201], v156 offset:35840
	ds_read_b128 v[202:205], v156 offset:36864
	ds_read_b128 v[206:209], v156 offset:37888
	ds_read_b128 v[210:213], v156 offset:38912
	ds_read_b128 v[214:217], v156 offset:39936
	s_waitcnt vmcnt(8)
	s_waitcnt lgkmcnt(0)
	s_barrier
	s_setprio 1
	v_mfma_f32_16x16x32_bf16 v[124:127], v[144:147], v[186:189], v[124:127]
	v_mfma_f32_16x16x32_bf16 v[120:123], v[162:165], v[186:189], v[120:123]
	v_mfma_f32_16x16x32_bf16 v[108:111], v[144:147], v[194:197], v[108:111]
	v_mfma_f32_16x16x32_bf16 v[104:107], v[162:165], v[194:197], v[104:107]
	v_mfma_f32_16x16x32_bf16 v[92:95], v[144:147], v[202:205], v[92:95]
	v_mfma_f32_16x16x32_bf16 v[88:91], v[162:165], v[202:205], v[88:91]
	v_mfma_f32_16x16x32_bf16 v[76:79], v[144:147], v[210:213], v[76:79]
	v_mfma_f32_16x16x32_bf16 v[72:75], v[162:165], v[210:213], v[72:75]
	v_mfma_f32_16x16x32_bf16 v[124:127], v[158:161], v[190:193], v[124:127]
	v_mfma_f32_16x16x32_bf16 v[120:123], v[166:169], v[190:193], v[120:123]
	v_mfma_f32_16x16x32_bf16 v[108:111], v[158:161], v[198:201], v[108:111]
	v_mfma_f32_16x16x32_bf16 v[104:107], v[166:169], v[198:201], v[104:107]
	v_mfma_f32_16x16x32_bf16 v[92:95], v[158:161], v[206:209], v[92:95]
	v_mfma_f32_16x16x32_bf16 v[88:91], v[166:169], v[206:209], v[88:91]
	v_mfma_f32_16x16x32_bf16 v[76:79], v[158:161], v[214:217], v[76:79]
	v_mfma_f32_16x16x32_bf16 v[72:75], v[166:169], v[214:217], v[72:75]
	s_setprio 0
	s_setprio 1
	v_mfma_f32_16x16x32_bf16 v[116:119], v[170:173], v[186:189], v[116:119]
	v_mfma_f32_16x16x32_bf16 v[112:115], v[178:181], v[186:189], v[112:115]
	v_mfma_f32_16x16x32_bf16 v[100:103], v[170:173], v[194:197], v[100:103]
	v_mfma_f32_16x16x32_bf16 v[96:99], v[178:181], v[194:197], v[96:99]
	v_mfma_f32_16x16x32_bf16 v[84:87], v[170:173], v[202:205], v[84:87]
	v_mfma_f32_16x16x32_bf16 v[80:83], v[178:181], v[202:205], v[80:83]
	v_mfma_f32_16x16x32_bf16 v[68:71], v[170:173], v[210:213], v[68:71]
	v_mfma_f32_16x16x32_bf16 v[64:67], v[178:181], v[210:213], v[64:67]
	v_mfma_f32_16x16x32_bf16 v[116:119], v[174:177], v[190:193], v[116:119]
	v_mfma_f32_16x16x32_bf16 v[112:115], v[182:185], v[190:193], v[112:115]
	v_mfma_f32_16x16x32_bf16 v[100:103], v[174:177], v[198:201], v[100:103]
	v_mfma_f32_16x16x32_bf16 v[96:99], v[182:185], v[198:201], v[96:99]
	v_mfma_f32_16x16x32_bf16 v[84:87], v[174:177], v[206:209], v[84:87]
	v_mfma_f32_16x16x32_bf16 v[80:83], v[182:185], v[206:209], v[80:83]
	v_mfma_f32_16x16x32_bf16 v[68:71], v[174:177], v[214:217], v[68:71]
	v_mfma_f32_16x16x32_bf16 v[64:67], v[182:185], v[214:217], v[64:67]
	s_setprio 0
	s_barrier
	s_mov_b32 m0, s44
	ds_read_b128 v[198:201], v156 offset:52224
	global_load_lds_dwordx4 v134, s[100:101]
	s_mov_b32 m0, s45
	ds_read_b128 v[202:205], v156 offset:53248
	global_load_lds_dwordx4 v130, s[100:101]
	s_add_i32 s28, s59, s0
	s_mov_b32 m0, s28
	ds_read_b128 v[186:189], v156 offset:49152
	global_load_lds_dwordx4 v132, s[98:99]
	s_add_i32 m0, s28, 0x2000
	s_add_u32 s26, s26, 0x40080
	s_addc_u32 s27, s27, 0
	s_add_i32 s28, s60, s0
	global_load_lds_dwordx4 v128, s[98:99]
	s_mov_b32 m0, s28
	ds_read_b128 v[190:193], v156 offset:50176
	global_load_lds_dwordx4 v132, s[26:27]
	s_add_i32 m0, s28, 0x2000
	ds_read_b128 v[194:197], v156 offset:51200
	global_load_lds_dwordx4 v128, s[26:27]
	ds_read_b128 v[206:209], v156 offset:54272
	ds_read_b128 v[210:213], v156 offset:55296
	ds_read_b128 v[214:217], v156 offset:56320
	s_waitcnt vmcnt(8)
	s_waitcnt lgkmcnt(0)
	s_barrier
	s_setprio 1
	v_mfma_f32_16x16x32_bf16 v[60:63], v[144:147], v[186:189], v[60:63]
	v_mfma_f32_16x16x32_bf16 v[56:59], v[162:165], v[186:189], v[56:59]
	v_mfma_f32_16x16x32_bf16 v[44:47], v[144:147], v[194:197], v[44:47]
	v_mfma_f32_16x16x32_bf16 v[40:43], v[162:165], v[194:197], v[40:43]
	v_mfma_f32_16x16x32_bf16 v[28:31], v[144:147], v[202:205], v[28:31]
	v_mfma_f32_16x16x32_bf16 v[24:27], v[162:165], v[202:205], v[24:27]
	v_mfma_f32_16x16x32_bf16 v[12:15], v[144:147], v[210:213], v[12:15]
	v_mfma_f32_16x16x32_bf16 v[8:11], v[162:165], v[210:213], v[8:11]
	v_mfma_f32_16x16x32_bf16 v[60:63], v[158:161], v[190:193], v[60:63]
	v_mfma_f32_16x16x32_bf16 v[56:59], v[166:169], v[190:193], v[56:59]
	v_mfma_f32_16x16x32_bf16 v[44:47], v[158:161], v[198:201], v[44:47]
	v_mfma_f32_16x16x32_bf16 v[40:43], v[166:169], v[198:201], v[40:43]
	v_mfma_f32_16x16x32_bf16 v[28:31], v[158:161], v[206:209], v[28:31]
	v_mfma_f32_16x16x32_bf16 v[24:27], v[166:169], v[206:209], v[24:27]
	v_mfma_f32_16x16x32_bf16 v[12:15], v[158:161], v[214:217], v[12:15]
	v_mfma_f32_16x16x32_bf16 v[8:11], v[166:169], v[214:217], v[8:11]
	s_setprio 0
	s_setprio 1
	v_mfma_f32_16x16x32_bf16 v[52:55], v[170:173], v[186:189], v[52:55]
	v_mfma_f32_16x16x32_bf16 v[48:51], v[178:181], v[186:189], v[48:51]
	v_mfma_f32_16x16x32_bf16 v[36:39], v[170:173], v[194:197], v[36:39]
	v_mfma_f32_16x16x32_bf16 v[32:35], v[178:181], v[194:197], v[32:35]
	v_mfma_f32_16x16x32_bf16 v[20:23], v[170:173], v[202:205], v[20:23]
	v_mfma_f32_16x16x32_bf16 v[16:19], v[178:181], v[202:205], v[16:19]
	v_mfma_f32_16x16x32_bf16 v[4:7], v[170:173], v[210:213], v[4:7]
	v_mfma_f32_16x16x32_bf16 v[0:3], v[178:181], v[210:213], v[0:3]
	v_mfma_f32_16x16x32_bf16 v[52:55], v[174:177], v[190:193], v[52:55]
	v_mfma_f32_16x16x32_bf16 v[48:51], v[182:185], v[190:193], v[48:51]
	v_mfma_f32_16x16x32_bf16 v[36:39], v[174:177], v[198:201], v[36:39]
	v_mfma_f32_16x16x32_bf16 v[32:35], v[182:185], v[198:201], v[32:35]
	v_mfma_f32_16x16x32_bf16 v[20:23], v[174:177], v[206:209], v[20:23]
	v_mfma_f32_16x16x32_bf16 v[16:19], v[182:185], v[206:209], v[16:19]
	v_mfma_f32_16x16x32_bf16 v[4:7], v[174:177], v[214:217], v[4:7]
	v_mfma_f32_16x16x32_bf16 v[0:3], v[182:185], v[214:217], v[0:3]
	s_setprio 0
	s_barrier
	s_add_i32 s58, s58, 2
	s_add_u32 s24, s24, 0x100
	s_addc_u32 s25, s25, 0
	s_add_u32 s56, s56, 0x100
	s_addc_u32 s57, s57, 0
	s_cmp_gt_u32 s58, 13
	s_cbranch_scc0 .LBB0_1238
	s_and_b64 vcc, exec, s[12:13]
	s_cbranch_vccz .LBB0_1241
	s_barrier

; #define PG8_STAGE(bufoff, gbase, voff) do { _Pragma("unroll") for (int _i = 0; _i < 2; ++_i) \
;         __builtin_amdgcn_global_load_lds((const unsigned*)((const char*)(gbase) + (voff)[_i]), (PG8_LAS unsigned*)(lds + (bufoff) + ldsw + _i * 8192), 16, 0, 0); } while (0)
; #define PG8_LDA(dst, b, h) do { _Pragma("unroll") for (int m = 0; m < 4; ++m) _Pragma("unroll") for (int k = 0; k < 2; ++k) dst[m][k] = *(const PG8_LAS bf16x8*)(lds + PG8_SA(b, h) + aoff + m * 2048 + k * 1024); } while (0)
; #define PG8_LDB(dst, b, h) do { _Pragma("unroll") for (int n = 0; n < 2; ++n) _Pragma("unroll") for (int k = 0; k < 2; ++k) dst[n][k] = *(const PG8_LAS bf16x8*)(lds + PG8_SB(b, h) + boff + n * 2048 + k * 1024); } while (0)
; #define PG8_MMA(ai, bj, At, Bt) do { __builtin_amdgcn_s_setprio(1); _Pragma("unroll") for (int m = 0; m < 4; ++m) _Pragma("unroll") for (int n = 0; n < 2; ++n) _Pragma("unroll") for (int k = 0; k < 2; ++k) \
;         acc[ai][bj][m][n] = __builtin_amdgcn_mfma_f32_16x16x32_bf16(Bt[n][k], At[m][k], acc[ai][bj][m][n], 0, 0, 0); __builtin_amdgcn_s_setprio(0); } while (0)
; #define PG8_WAIT_V(n) asm volatile("s_waitcnt vmcnt(" #n ")" ::: "memory")
; #define PG8_WAIT_L(n) asm volatile("s_waitcnt lgkmcnt(" #n ")" ::: "memory")
; template <class Epi, class Sched, bool ALIGN_EPI = false, bool SP2 = false>
; __device__ __forceinline__ void gemm_phase(PG8_LAS unsigned char* lds, const Gemm g, const Sched& S, const Epi& E, int tid_in) {
;     ...
;             const bool last = (t == nt - 2);
;             const char* a1 = cA + (size_t)(t + 1) * kstep;
;             const char* a2 = last ? nA : cA + (size_t)(t + 2) * kstep; const char* b2 = last ? nB : cB + (size_t)(t + 2) * kstep;
;             const char* a3 = a2 + kstep; const char* b3 = b2 + kstep;
;             if (last && has_next) S.a_ready(nxt);
;             if constexpr (SP2) {
;             PG8_LDB(B0, 0, 0); PG8_LDB(B1, 0, 1); PG8_SCHED; PG8_LDA(At, 0, 0); PG8_STAGE(PG8_SA(1, 1), a1 + hstep, voffA);
;             PG8_WAIT_V(8); PG8_WAIT_L(0); PG8_BAR; PG8_MMA(0, 0, At, B0); PG8_MMA(0, 1, At, B1); PG8_BAR; PG8_SCHED;
;             PG8_LDA(At, 0, 1); PG8_STAGE(PG8_SB(0, 0), b2, voffB); PG8_STAGE(PG8_SB(0, 1), b2 + hstep, voffB); PG8_STAGE(PG8_SA(0, 0), a2, voffA);
;             PG8_WAIT_V(8); PG8_WAIT_L(0); PG8_BAR; PG8_MMA(1, 0, At, B0); PG8_MMA(1, 1, At, B1); PG8_BAR; PG8_SCHED;
.LBB0_1321:
	s_add_u32 s2, s20, 0x100
	s_addc_u32 s3, s21, 0
	s_cmp_eq_u32 s50, 40
	s_cselect_b32 s25, s17, s3
	s_cselect_b32 s24, s16, s2
	s_cselect_b32 s23, s19, s49
	s_cselect_b32 s22, s18, s48
	s_add_i32 m0, s34, 0xc000
	ds_read_b128 v[128:131], v195
	global_load_lds_dwordx4 v168, s[20:21]
	s_add_i32 m0, s34, 0xe000
	ds_read_b128 v[132:135], v195 offset:1024
	global_load_lds_dwordx4 v170, s[20:21]
	ds_read_b128 v[136:139], v195 offset:2048
	ds_read_b128 v[140:143], v195 offset:3072
	ds_read_b128 v[144:147], v196
	ds_read_b128 v[148:151], v196 offset:1024
	ds_read_b128 v[152:155], v196 offset:2048
	ds_read_b128 v[156:159], v196 offset:3072
	ds_read_b128 v[176:179], v197
	ds_read_b128 v[180:183], v197 offset:1024
	ds_read_b128 v[184:187], v197 offset:2048
	ds_read_b128 v[188:191], v197 offset:3072
	ds_read_b128 v[198:201], v197 offset:4096
	ds_read_b128 v[202:205], v197 offset:5120
	ds_read_b128 v[206:209], v197 offset:6144
	ds_read_b128 v[210:213], v197 offset:7168
	s_waitcnt vmcnt(8)
	s_waitcnt lgkmcnt(0)
	s_barrier
	s_setprio 1
	v_mfma_f32_16x16x32_bf16 v[120:123], v[128:131], v[176:179], v[120:123]
	v_mfma_f32_16x16x32_bf16 v[124:127], v[136:139], v[176:179], v[124:127]
	v_mfma_f32_16x16x32_bf16 v[104:107], v[128:131], v[184:187], v[104:107]
	v_mfma_f32_16x16x32_bf16 v[108:111], v[136:139], v[184:187], v[108:111]
	v_mfma_f32_16x16x32_bf16 v[88:91], v[128:131], v[198:201], v[88:91]
	v_mfma_f32_16x16x32_bf16 v[92:95], v[136:139], v[198:201], v[92:95]
	v_mfma_f32_16x16x32_bf16 v[72:75], v[128:131], v[206:209], v[72:75]
	v_mfma_f32_16x16x32_bf16 v[76:79], v[136:139], v[206:209], v[76:79]
	v_mfma_f32_16x16x32_bf16 v[120:123], v[132:135], v[180:183], v[120:123]
	v_mfma_f32_16x16x32_bf16 v[124:127], v[140:143], v[180:183], v[124:127]
	v_mfma_f32_16x16x32_bf16 v[104:107], v[132:135], v[188:191], v[104:107]
	v_mfma_f32_16x16x32_bf16 v[108:111], v[140:143], v[188:191], v[108:111]
	v_mfma_f32_16x16x32_bf16 v[88:91], v[132:135], v[202:205], v[88:91]
	v_mfma_f32_16x16x32_bf16 v[92:95], v[140:143], v[202:205], v[92:95]
	v_mfma_f32_16x16x32_bf16 v[72:75], v[132:135], v[210:213], v[72:75]
	v_mfma_f32_16x16x32_bf16 v[76:79], v[140:143], v[210:213], v[76:79]
	s_setprio 0
	s_setprio 1
	v_mfma_f32_16x16x32_bf16 v[112:115], v[144:147], v[176:179], v[112:115]
	v_mfma_f32_16x16x32_bf16 v[116:119], v[152:155], v[176:179], v[116:119]
	v_mfma_f32_16x16x32_bf16 v[96:99], v[144:147], v[184:187], v[96:99]
	v_mfma_f32_16x16x32_bf16 v[100:103], v[152:155], v[184:187], v[100:103]
	v_mfma_f32_16x16x32_bf16 v[80:83], v[144:147], v[198:201], v[80:83]
	v_mfma_f32_16x16x32_bf16 v[84:87], v[152:155], v[198:201], v[84:87]
	v_mfma_f32_16x16x32_bf16 v[64:67], v[144:147], v[206:209], v[64:67]
	v_mfma_f32_16x16x32_bf16 v[68:71], v[152:155], v[206:209], v[68:71]
	v_mfma_f32_16x16x32_bf16 v[112:115], v[148:151], v[180:183], v[112:115]
	v_mfma_f32_16x16x32_bf16 v[116:119], v[156:159], v[180:183], v[116:119]
	v_mfma_f32_16x16x32_bf16 v[96:99], v[148:151], v[188:191], v[96:99]
	v_mfma_f32_16x16x32_bf16 v[100:103], v[156:159], v[188:191], v[100:103]
	v_mfma_f32_16x16x32_bf16 v[80:83], v[148:151], v[202:205], v[80:83]
	v_mfma_f32_16x16x32_bf16 v[84:87], v[156:159], v[202:205], v[84:87]
	v_mfma_f32_16x16x32_bf16 v[64:67], v[148:151], v[210:213], v[64:67]
	v_mfma_f32_16x16x32_bf16 v[68:71], v[156:159], v[210:213], v[68:71]
	s_setprio 0
	s_barrier
	s_add_u32 s98, s22, s10
	s_addc_u32 s99, s23, s11
	s_add_u32 s100, s24, s10
	s_addc_u32 s101, s25, s11
	s_mov_b32 m0, s34
	ds_read_b128 v[188:191], v197 offset:19456
	global_load_lds_dwordx4 v160, s[24:25]
	s_mov_b32 m0, s35
	ds_read_b128 v[198:201], v197 offset:20480
	global_load_lds_dwordx4 v164, s[24:25]
	s_add_i32 s20, s42, s31
	s_mov_b32 m0, s20
	ds_read_b128 v[176:179], v197 offset:16384
	global_load_lds_dwordx4 v162, s[22:23]
	s_add_i32 m0, s20, 0x2000
	s_add_u32 s20, s22, 0xb0000
	s_addc_u32 s21, s23, 0
	s_add_i32 s51, s43, s31
	global_load_lds_dwordx4 v166, s[22:23]
	s_mov_b32 m0, s51
	ds_read_b128 v[180:183], v197 offset:17408
	global_load_lds_dwordx4 v162, s[20:21]
	s_add_i32 m0, s51, 0x2000
	ds_read_b128 v[184:187], v197 offset:18432
	global_load_lds_dwordx4 v166, s[20:21]
	ds_read_b128 v[202:205], v197 offset:21504
	ds_read_b128 v[206:209], v197 offset:22528
	ds_read_b128 v[210:213], v197 offset:23552
	s_waitcnt vmcnt(8)
	s_waitcnt lgkmcnt(0)
	s_barrier
	s_setprio 1
	v_mfma_f32_16x16x32_bf16 v[56:59], v[128:131], v[176:179], v[56:59]
	v_mfma_f32_16x16x32_bf16 v[60:63], v[136:139], v[176:179], v[60:63]
	v_mfma_f32_16x16x32_bf16 v[40:43], v[128:131], v[184:187], v[40:43]
	v_mfma_f32_16x16x32_bf16 v[44:47], v[136:139], v[184:187], v[44:47]
	v_mfma_f32_16x16x32_bf16 v[24:27], v[128:131], v[198:201], v[24:27]
	v_mfma_f32_16x16x32_bf16 v[28:31], v[136:139], v[198:201], v[28:31]
	v_mfma_f32_16x16x32_bf16 v[8:11], v[128:131], v[206:209], v[8:11]
	v_mfma_f32_16x16x32_bf16 v[12:15], v[136:139], v[206:209], v[12:15]
	v_mfma_f32_16x16x32_bf16 v[56:59], v[132:135], v[180:183], v[56:59]
	v_mfma_f32_16x16x32_bf16 v[60:63], v[140:143], v[180:183], v[60:63]
	v_mfma_f32_16x16x32_bf16 v[40:43], v[132:135], v[188:191], v[40:43]
	v_mfma_f32_16x16x32_bf16 v[44:47], v[140:143], v[188:191], v[44:47]
	v_mfma_f32_16x16x32_bf16 v[24:27], v[132:135], v[202:205], v[24:27]
	v_mfma_f32_16x16x32_bf16 v[28:31], v[140:143], v[202:205], v[28:31]
	v_mfma_f32_16x16x32_bf16 v[8:11], v[132:135], v[210:213], v[8:11]
	v_mfma_f32_16x16x32_bf16 v[12:15], v[140:143], v[210:213], v[12:15]
	s_setprio 0
	s_setprio 1
	v_mfma_f32_16x16x32_bf16 v[48:51], v[144:147], v[176:179], v[48:51]
	v_mfma_f32_16x16x32_bf16 v[52:55], v[152:155], v[176:179], v[52:55]
	v_mfma_f32_16x16x32_bf16 v[32:35], v[144:147], v[184:187], v[32:35]
	v_mfma_f32_16x16x32_bf16 v[36:39], v[152:155], v[184:187], v[36:39]
	v_mfma_f32_16x16x32_bf16 v[16:19], v[144:147], v[198:201], v[16:19]
	v_mfma_f32_16x16x32_bf16 v[20:23], v[152:155], v[198:201], v[20:23]
	v_mfma_f32_16x16x32_bf16 v[4:7], v[144:147], v[206:209], v[4:7]
	v_mfma_f32_16x16x32_bf16 v[0:3], v[152:155], v[206:209], v[0:3]
	v_mfma_f32_16x16x32_bf16 v[48:51], v[148:151], v[180:183], v[48:51]
	v_mfma_f32_16x16x32_bf16 v[52:55], v[156:159], v[180:183], v[52:55]
	v_mfma_f32_16x16x32_bf16 v[32:35], v[148:151], v[188:191], v[32:35]
	v_mfma_f32_16x16x32_bf16 v[36:39], v[156:159], v[188:191], v[36:39]
	v_mfma_f32_16x16x32_bf16 v[16:19], v[148:151], v[202:205], v[16:19]
	v_mfma_f32_16x16x32_bf16 v[20:23], v[156:159], v[202:205], v[20:23]
	v_mfma_f32_16x16x32_bf16 v[4:7], v[148:151], v[210:213], v[4:7]
	v_mfma_f32_16x16x32_bf16 v[0:3], v[156:159], v[210:213], v[0:3]
	s_setprio 0
	s_barrier
; #define PG8_STAGE(bufoff, gbase, voff) do { _Pragma("unroll") for (int _i = 0; _i < 2; ++_i) \
;         __builtin_amdgcn_global_load_lds((const unsigned*)((const char*)(gbase) + (voff)[_i]), (PG8_LAS unsigned*)(lds + (bufoff) + ldsw + _i * 8192), 16, 0, 0); } while (0)
; #define PG8_LDA(dst, b, h) do { _Pragma("unroll") for (int m = 0; m < 4; ++m) _Pragma("unroll") for (int k = 0; k < 2; ++k) dst[m][k] = *(const PG8_LAS bf16x8*)(lds + PG8_SA(b, h) + aoff + m * 2048 + k * 1024); } while (0)
; #define PG8_LDB(dst, b, h) do { _Pragma("unroll") for (int n = 0; n < 2; ++n) _Pragma("unroll") for (int k = 0; k < 2; ++k) dst[n][k] = *(const PG8_LAS bf16x8*)(lds + PG8_SB(b, h) + boff + n * 2048 + k * 1024); } while (0)
; #define PG8_MMA(ai, bj, At, Bt) do { __builtin_amdgcn_s_setprio(1); _Pragma("unroll") for (int m = 0; m < 4; ++m) _Pragma("unroll") for (int n = 0; n < 2; ++n) _Pragma("unroll") for (int k = 0; k < 2; ++k) \
;         acc[ai][bj][m][n] = __builtin_amdgcn_mfma_f32_16x16x32_bf16(Bt[n][k], At[m][k], acc[ai][bj][m][n], 0, 0, 0); __builtin_amdgcn_s_setprio(0); } while (0)
; #define PG8_WAIT_V(n) asm volatile("s_waitcnt vmcnt(" #n ")" ::: "memory")
; #define PG8_WAIT_L(n) asm volatile("s_waitcnt lgkmcnt(" #n ")" ::: "memory")
; #define PG8_BAR __builtin_amdgcn_s_barrier()
; #define PG8_SCHED __builtin_amdgcn_sched_barrier(0)
; template <class Epi, class Sched, bool ALIGN_EPI = false, bool SP2 = false>
; __device__ __forceinline__ void gemm_phase(PG8_LAS unsigned char* lds, const Gemm g, const Sched& S, const Epi& E, int tid_in) {
;     ...
;             PG8_LDB(B0, 1, 0); PG8_LDB(B1, 1, 1); PG8_SCHED; PG8_LDA(At, 1, 0); PG8_STAGE(PG8_SA(0, 1), a2 + hstep, voffA);
;             PG8_WAIT_V(8); PG8_WAIT_L(0); PG8_BAR; PG8_MMA(0, 0, At, B0); PG8_MMA(0, 1, At, B1); PG8_BAR; PG8_SCHED;
;             PG8_LDA(At, 1, 1); PG8_STAGE(PG8_SB(1, 0), b3, voffB); PG8_STAGE(PG8_SB(1, 1), b3 + hstep, voffB); PG8_STAGE(PG8_SA(1, 0), a3, voffA);
;             PG8_WAIT_V(8); PG8_WAIT_L(0); PG8_BAR; PG8_MMA(1, 0, At, B0); PG8_MMA(1, 1, At, B1); PG8_BAR; PG8_SCHED;
	s_add_i32 s51, 0, 0x18000
	s_add_i32 s52, 0, 0x1c000
	s_add_u32 s20, s24, 0xb0000
	s_addc_u32 s21, s25, 0
	s_mov_b32 m0, s36
	s_nop 0
	global_load_lds_dwordx4 v160, s[20:21]
	s_mov_b32 m0, s37
	s_nop 0
	global_load_lds_dwordx4 v164, s[20:21]
	v_add_u32_e32 v140, s51, v193
	v_add_u32_e32 v156, s52, v193
	ds_read_b128 v[128:131], v140
	ds_read_b128 v[132:135], v140 offset:1024
	ds_read_b128 v[136:139], v140 offset:2048
	ds_read_b128 v[140:143], v140 offset:3072
	ds_read_b128 v[144:147], v156
	ds_read_b128 v[148:151], v156 offset:1024
	ds_read_b128 v[152:155], v156 offset:2048
	ds_read_b128 v[156:159], v156 offset:3072
	ds_read_b128 v[176:179], v197 offset:32768
	ds_read_b128 v[180:183], v197 offset:33792
	ds_read_b128 v[184:187], v197 offset:34816
	ds_read_b128 v[188:191], v197 offset:35840
	ds_read_b128 v[198:201], v197 offset:36864
	ds_read_b128 v[202:205], v197 offset:37888
	ds_read_b128 v[206:209], v197 offset:38912
	ds_read_b128 v[210:213], v197 offset:39936
	s_waitcnt vmcnt(8)
	s_waitcnt lgkmcnt(0)
	s_barrier
	s_setprio 1
	v_mfma_f32_16x16x32_bf16 v[120:123], v[128:131], v[176:179], v[120:123]
	v_mfma_f32_16x16x32_bf16 v[124:127], v[136:139], v[176:179], v[124:127]
	v_mfma_f32_16x16x32_bf16 v[104:107], v[128:131], v[184:187], v[104:107]
	v_mfma_f32_16x16x32_bf16 v[108:111], v[136:139], v[184:187], v[108:111]
	v_mfma_f32_16x16x32_bf16 v[88:91], v[128:131], v[198:201], v[88:91]
	v_mfma_f32_16x16x32_bf16 v[92:95], v[136:139], v[198:201], v[92:95]
	v_mfma_f32_16x16x32_bf16 v[72:75], v[128:131], v[206:209], v[72:75]
	v_mfma_f32_16x16x32_bf16 v[76:79], v[136:139], v[206:209], v[76:79]
	v_mfma_f32_16x16x32_bf16 v[120:123], v[132:135], v[180:183], v[120:123]
	v_mfma_f32_16x16x32_bf16 v[124:127], v[140:143], v[180:183], v[124:127]
	v_mfma_f32_16x16x32_bf16 v[104:107], v[132:135], v[188:191], v[104:107]
	v_mfma_f32_16x16x32_bf16 v[108:111], v[140:143], v[188:191], v[108:111]
	v_mfma_f32_16x16x32_bf16 v[88:91], v[132:135], v[202:205], v[88:91]
	v_mfma_f32_16x16x32_bf16 v[92:95], v[140:143], v[202:205], v[92:95]
	v_mfma_f32_16x16x32_bf16 v[72:75], v[132:135], v[210:213], v[72:75]
	v_mfma_f32_16x16x32_bf16 v[76:79], v[140:143], v[210:213], v[76:79]
	s_setprio 0
	s_setprio 1
	v_mfma_f32_16x16x32_bf16 v[112:115], v[144:147], v[176:179], v[112:115]
	v_mfma_f32_16x16x32_bf16 v[116:119], v[152:155], v[176:179], v[116:119]
	v_mfma_f32_16x16x32_bf16 v[96:99], v[144:147], v[184:187], v[96:99]
	v_mfma_f32_16x16x32_bf16 v[100:103], v[152:155], v[184:187], v[100:103]
	v_mfma_f32_16x16x32_bf16 v[80:83], v[144:147], v[198:201], v[80:83]
	v_mfma_f32_16x16x32_bf16 v[84:87], v[152:155], v[198:201], v[84:87]
	v_mfma_f32_16x16x32_bf16 v[64:67], v[144:147], v[206:209], v[64:67]
	v_mfma_f32_16x16x32_bf16 v[68:71], v[152:155], v[206:209], v[68:71]
	v_mfma_f32_16x16x32_bf16 v[112:115], v[148:151], v[180:183], v[112:115]
	v_mfma_f32_16x16x32_bf16 v[116:119], v[156:159], v[180:183], v[116:119]
	v_mfma_f32_16x16x32_bf16 v[96:99], v[148:151], v[188:191], v[96:99]
	v_mfma_f32_16x16x32_bf16 v[100:103], v[156:159], v[188:191], v[100:103]
	v_mfma_f32_16x16x32_bf16 v[80:83], v[148:151], v[202:205], v[80:83]
	v_mfma_f32_16x16x32_bf16 v[84:87], v[156:159], v[202:205], v[84:87]
	v_mfma_f32_16x16x32_bf16 v[64:67], v[148:151], v[210:213], v[64:67]
	v_mfma_f32_16x16x32_bf16 v[68:71], v[156:159], v[210:213], v[68:71]
	s_setprio 0
	s_barrier
	s_mov_b32 m0, s39
	ds_read_b128 v[188:191], v197 offset:52224
	global_load_lds_dwordx4 v160, s[100:101]
	s_mov_b32 m0, s40
	ds_read_b128 v[198:201], v197 offset:53248
	global_load_lds_dwordx4 v164, s[100:101]
	s_add_i32 s20, s51, s31
	s_mov_b32 m0, s20
	ds_read_b128 v[176:179], v197 offset:49152
	global_load_lds_dwordx4 v162, s[98:99]
	s_add_i32 m0, s20, 0x2000
	s_add_u32 s20, s22, 0xb0080
	s_addc_u32 s21, s23, 0
	s_add_i32 s22, s52, s31
	global_load_lds_dwordx4 v166, s[98:99]
	s_mov_b32 m0, s22
	ds_read_b128 v[180:183], v197 offset:50176
	global_load_lds_dwordx4 v162, s[20:21]
	s_add_i32 m0, s22, 0x2000
	ds_read_b128 v[184:187], v197 offset:51200
	global_load_lds_dwordx4 v166, s[20:21]
	ds_read_b128 v[202:205], v197 offset:54272
	ds_read_b128 v[206:209], v197 offset:55296
	ds_read_b128 v[210:213], v197 offset:56320
	s_waitcnt vmcnt(8)
	s_waitcnt lgkmcnt(0)
	s_barrier
	s_setprio 1
	v_mfma_f32_16x16x32_bf16 v[56:59], v[128:131], v[176:179], v[56:59]
	v_mfma_f32_16x16x32_bf16 v[60:63], v[136:139], v[176:179], v[60:63]
	v_mfma_f32_16x16x32_bf16 v[40:43], v[128:131], v[184:187], v[40:43]
	v_mfma_f32_16x16x32_bf16 v[44:47], v[136:139], v[184:187], v[44:47]
	v_mfma_f32_16x16x32_bf16 v[24:27], v[128:131], v[198:201], v[24:27]
	v_mfma_f32_16x16x32_bf16 v[28:31], v[136:139], v[198:201], v[28:31]
	v_mfma_f32_16x16x32_bf16 v[8:11], v[128:131], v[206:209], v[8:11]
	v_mfma_f32_16x16x32_bf16 v[12:15], v[136:139], v[206:209], v[12:15]
	v_mfma_f32_16x16x32_bf16 v[56:59], v[132:135], v[180:183], v[56:59]
	v_mfma_f32_16x16x32_bf16 v[60:63], v[140:143], v[180:183], v[60:63]
	v_mfma_f32_16x16x32_bf16 v[40:43], v[132:135], v[188:191], v[40:43]
	v_mfma_f32_16x16x32_bf16 v[44:47], v[140:143], v[188:191], v[44:47]
	v_mfma_f32_16x16x32_bf16 v[24:27], v[132:135], v[202:205], v[24:27]
	v_mfma_f32_16x16x32_bf16 v[28:31], v[140:143], v[202:205], v[28:31]
	v_mfma_f32_16x16x32_bf16 v[8:11], v[132:135], v[210:213], v[8:11]
	v_mfma_f32_16x16x32_bf16 v[12:15], v[140:143], v[210:213], v[12:15]
	s_setprio 0
	s_setprio 1
	v_mfma_f32_16x16x32_bf16 v[48:51], v[144:147], v[176:179], v[48:51]
	v_mfma_f32_16x16x32_bf16 v[52:55], v[152:155], v[176:179], v[52:55]
	v_mfma_f32_16x16x32_bf16 v[32:35], v[144:147], v[184:187], v[32:35]
	v_mfma_f32_16x16x32_bf16 v[36:39], v[152:155], v[184:187], v[36:39]
	v_mfma_f32_16x16x32_bf16 v[16:19], v[144:147], v[198:201], v[16:19]
	v_mfma_f32_16x16x32_bf16 v[20:23], v[152:155], v[198:201], v[20:23]
	v_mfma_f32_16x16x32_bf16 v[4:7], v[144:147], v[206:209], v[4:7]
	v_mfma_f32_16x16x32_bf16 v[0:3], v[152:155], v[206:209], v[0:3]
	v_mfma_f32_16x16x32_bf16 v[48:51], v[148:151], v[180:183], v[48:51]
	v_mfma_f32_16x16x32_bf16 v[52:55], v[156:159], v[180:183], v[52:55]
	v_mfma_f32_16x16x32_bf16 v[32:35], v[148:151], v[188:191], v[32:35]
	v_mfma_f32_16x16x32_bf16 v[36:39], v[156:159], v[188:191], v[36:39]
	v_mfma_f32_16x16x32_bf16 v[16:19], v[148:151], v[202:205], v[16:19]
	v_mfma_f32_16x16x32_bf16 v[20:23], v[156:159], v[202:205], v[20:23]
	v_mfma_f32_16x16x32_bf16 v[4:7], v[148:151], v[210:213], v[4:7]
	v_mfma_f32_16x16x32_bf16 v[0:3], v[156:159], v[210:213], v[0:3]
	s_setprio 0
	s_barrier
	s_add_i32 s50, s50, 2
	s_add_u32 s48, s48, 0x100
	s_addc_u32 s49, s49, 0
	s_cmp_gt_u32 s50, 41
	s_mov_b64 s[20:21], s[2:3]
	s_cbranch_scc0 .LBB0_1321
	s_and_b64 vcc, exec, s[12:13]
	s_cbranch_vccz .LBB0_1324
	s_barrier
